# attention K/V LDS-DMA source pointers moved to one SGPR base + 32-bit VGPR offsets: 6 v_lshl_add_u64 per iteration replaced by SALU adds
# speedup vs baseline: 1.1087x; 1.0211x over previous
; __device__ __forceinline__ void attn_item(const bf16_t* __restrict__ Qb, const bf16_t* __restrict__ Kh, const bf16_t* __restrict__ Vh, const bf16_t* __restrict__ Zb, ...
;     ...
;   float m_reg = 0.f, l_reg = 0; f32x16 o[4] = {}; bf16x8 qr[8]; f32x16 negm = f32x16{}; asm volatile("" : "+v"(negm));
;   const bf16_t* Qw = Qb + (long)(wid * QBLK + r32) * LDQ + hi * 8;
;   float qn2 = 0.f;
;   {
;     u32x4 qw[8];
; #pragma unroll
;     for (int d0 = 0; d0 < 8; ++d0) qw[d0] = *reinterpret_cast<const u32x4*>(Qw + d0 * 16);
;     float ss = 0.f;
; #pragma unroll
;     for (int d0 = 0; d0 < 8; ++d0) { const float a0 = bflo(qw[d0].x), a1 = bfhi(qw[d0].x), a2 = bflo(qw[d0].y), a3 = bfhi(qw[d0].y), a4 = bflo(qw[d0].z), a5 = bfhi(qw[d0].z), a6 = bflo(qw[d0].w), a7 = bfhi(qw[d0].w);
;       ss += (a0 * a0 + a1 * a1) + (a2 * a2 + a3 * a3) + (a4 * a4 + a5 * a5) + (a6 * a6 + a7 * a7); }
;     { auto rr = __builtin_amdgcn_permlane32_swap(__float_as_uint(ss), __float_as_uint(ss), false, false); ss = __uint_as_float(rr[0]) + __uint_as_float(rr[1]); }
;     const float rstd = __builtin_amdgcn_rsqf(ss * (1.0f / 128.0f) + NORM_EPS) * (SCALE * 1.4426950408889634f);
;     const int hq = lane_id_asm() >> 5;
;     const int spos = qpos0 + wid * QBLK + r32; const float prow = (float)(spos >> 6), pcol = (float)(spos & 63);
; #pragma unroll
;     for (int bb = 0; bb < 4; ++bb) { const int d1 = (bb & 1) + 4 * (bb >> 1), d2 = d1 + 2;
;       const float pos = (bb < 2) ? prow : pcol; const float* g1p = qg + d1 * 16 + hq * 8; const float* g2p = qg + d2 * 16 + hq * 8;
;       const f32x4 g1a = *(const f32x4*)g1p, g1b = *(const f32x4*)(g1p + 4), g2a = *(const f32x4*)g2p, g2b = *(const f32x4*)(g2p + 4);
;       float o1[8], o2[8];
; #pragma unroll
;       for (int e = 0; e < 8; ++e) { const unsigned w1 = (e < 2) ? qw[d1].x : (e < 4) ? qw[d1].y : (e < 6) ? qw[d1].z : qw[d1].w, w2 = (e < 2) ? qw[d2].x : (e < 4) ? qw[d2].y : (e < 6) ? qw[d2].z : qw[d2].w;
;         const float x1 = (e & 1) ? bfhi(w1) : bflo(w1), x2 = (e & 1) ? bfhi(w2) : bflo(w2); const float ga = (e < 4) ? g1a[e & 3] : g1b[e & 3], gb = (e < 4) ? g2a[e & 3] : g2b[e & 3];
;         const int fi = (d1 & 1) * 16 + hq * 8 + e; float rev = pos * (__builtin_amdgcn_exp2f(-(float)fi * (13.287712379549449f / 32.0f)) * 0.15915494309189535f); rev -= floorf(rev);
.LBB0_452:
	s_lshl_b32 s0, s70, 5
	s_and_b32 s0, s0, 32
	s_bfe_u32 s7, s70, 0x50003
	s_or_b32 s7, s0, s7
	s_lshl_b32 s0, s70, 12
	s_and_b32 s0, s0, 0x4000
	s_lshl_b32 s7, s7, 8
	s_bfe_u32 s1, s70, 0x10001
	s_or_b32 s71, s7, s0
	s_bfe_u32 s6, s54, 0x1000e
	s_lshl_b32 s8, s1, 8
	s_mul_i32 s9, s71, 0x2080
	s_add_u32 s9, s42, s9
	s_addc_u32 s36, s43, 0
	s_ashr_i32 s24, s70, 1
	s_lshl_b32 s1, s1, 9
	s_and_b32 s24, s24, 0xffffff80
	s_add_i32 s24, s1, s24
	s_ashr_i32 s25, s24, 31
	s_lshl_b64 s[26:27], s[24:25], 1
	s_add_u32 s24, s9, s26
	v_mbcnt_lo_u32_b32 v0, -1, 0
	v_mbcnt_hi_u32_b32 v0, -1, v0
	s_addc_u32 s25, s36, s27
	v_add_u32_e32 v186, s33, v0
	v_mov_b64_e32 v[2:3], s[24:25]
	v_ashrrev_i32_e32 v0, 1, v186
	v_and_b32_e32 v4, 0xffffffe0, v0
	v_bfi_b32 v0, s57, v0, v186
	v_lshrrev_b32_e32 v188, 1, v186
	v_mad_i64_i32 v[2:3], s[36:37], v0, s51, v[2:3]
	v_and_b32_e32 v212, 16, v188
	v_mov_b32_e32 v213, v1
	v_mov_b32_e32 v16, v1
	v_mov_b32_e32 v17, v1
	v_mov_b32_e32 v18, v1
	v_mov_b32_e32 v19, v1
	v_mov_b32_e32 v20, v1
	v_mov_b32_e32 v21, v1
	v_mov_b32_e32 v22, v1
	v_mov_b32_e32 v23, v1
	v_mov_b32_e32 v24, v1
	v_mov_b32_e32 v25, v1
	v_mov_b32_e32 v26, v1
	v_mov_b32_e32 v27, v1
	v_mov_b32_e32 v28, v1
	v_mov_b32_e32 v29, v1
	v_mov_b32_e32 v30, v1
	v_mov_b32_e32 v31, v1
	v_lshl_add_u64 v[2:3], v[2:3], 0, v[212:213]
	global_load_dwordx4 v[36:39], v[2:3], off
	global_load_dwordx4 v[44:47], v[2:3], off offset:32
	global_load_dwordx4 v[40:43], v[2:3], off offset:64
	global_load_dwordx4 v[48:51], v[2:3], off offset:96
	global_load_dwordx4 v[52:55], v[2:3], off offset:128
	global_load_dwordx4 v[60:63], v[2:3], off offset:160
	global_load_dwordx4 v[56:59], v[2:3], off offset:192
	global_load_dwordx4 v[64:67], v[2:3], off offset:224
	v_mbcnt_lo_u32_b32 v0, -1, 0
	v_mbcnt_hi_u32_b32 v0, -1, v0
	v_and_b32_e32 v187, 31, v186
	v_ashrrev_i32_e32 v0, 2, v0
	v_and_b32_e32 v78, -8, v0
	v_or_b32_e32 v69, 1, v78
	v_cvt_f32_i32_e32 v69, v69
	v_cvt_f32_i32_e32 v6, v78
	v_or_b32_e32 v2, s7, v187
	s_waitcnt vmcnt(22)
	v_add_u32_e32 v136, v2, v4
	v_mul_f32_e32 v69, 0xbed49a78, v69
	v_exp_f32_e32 v69, v69
	v_mul_f32_e32 v6, 0xbed49a78, v6
	v_ashrrev_i32_e32 v2, 6, v136
	v_exp_f32_e32 v68, v6
	v_mul_f32_e32 v138, 0.15915494, v69
	v_or_b32_e32 v69, 2, v78
	s_waitcnt vmcnt(20)
	v_cvt_f32_i32_e32 v145, v2
	v_cvt_f32_i32_e32 v69, v69
	v_ashrrev_i32_e32 v79, 31, v78
	v_lshl_add_u64 v[14:15], v[78:79], 2, s[18:19]
	global_load_dwordx4 v[10:13], v[14:15], off
	global_load_dwordx4 v[2:5], v[14:15], off offset:16
	global_load_dwordx4 v[32:35], v[14:15], off offset:128
	global_load_dwordx4 v[6:9], v[14:15], off offset:144
	v_mul_f32_e32 v137, 0.15915494, v68
	v_mul_f32_e32 v68, v137, v145
	v_mul_f32_e32 v69, 0xbed49a78, v69
	v_floor_f32_e32 v68, v68
	v_exp_f32_e32 v69, v69
	v_fma_f32 v68, v137, v145, -v68
	v_sin_f32_e32 v104, v68
	v_cos_f32_e32 v105, v68
	v_mul_f32_e32 v68, v138, v145
	v_floor_f32_e32 v68, v68
	v_fma_f32 v68, v138, v145, -v68
	v_mul_f32_e32 v139, 0.15915494, v69
	v_sin_f32_e32 v83, v68
	v_cos_f32_e32 v82, v68
	v_or_b32_e32 v68, 3, v78
	v_mul_f32_e32 v69, v139, v145
	v_cvt_f32_i32_e32 v68, v68
	v_floor_f32_e32 v69, v69
	v_fma_f32 v69, v139, v145, -v69
	v_sin_f32_e32 v106, v69
	v_cos_f32_e32 v107, v69
	v_or_b32_e32 v69, 4, v78
	v_cvt_f32_i32_e32 v69, v69
	v_mul_f32_e32 v68, 0xbed49a78, v68
	v_exp_f32_e32 v68, v68
	v_or_b32_e32 v0, 7, v0
	v_mul_f32_e32 v69, 0xbed49a78, v69
	v_exp_f32_e32 v69, v69
	v_mul_f32_e32 v140, 0.15915494, v68
	v_mul_f32_e32 v68, v140, v145
	v_floor_f32_e32 v68, v68
	v_fma_f32 v68, v140, v145, -v68
	v_mul_f32_e32 v141, 0.15915494, v69
	v_sin_f32_e32 v97, v68
	v_cos_f32_e32 v96, v68
	v_or_b32_e32 v68, 5, v78
	v_mul_f32_e32 v69, v141, v145
	v_cvt_f32_i32_e32 v68, v68
	v_floor_f32_e32 v69, v69
	v_fma_f32 v69, v141, v145, -v69
	v_sin_f32_e32 v108, v69
	v_cos_f32_e32 v109, v69
	v_or_b32_e32 v69, 6, v78
	v_cvt_f32_i32_e32 v69, v69
	v_mul_f32_e32 v68, 0xbed49a78, v68
	v_exp_f32_e32 v68, v68
	v_cvt_f32_i32_e32 v0, v0
	v_mul_f32_e32 v69, 0xbed49a78, v69
	v_exp_f32_e32 v69, v69
	v_mul_f32_e32 v142, 0.15915494, v68
	v_mul_f32_e32 v68, v142, v145
	v_floor_f32_e32 v68, v68
	v_fma_f32 v68, v142, v145, -v68
	v_mul_f32_e32 v143, 0.15915494, v69
	v_mul_f32_e32 v0, 0xbed49a78, v0
	v_sin_f32_e32 v101, v68
	v_cos_f32_e32 v100, v68
	v_mul_f32_e32 v68, v143, v145
	v_exp_f32_e32 v0, v0
	v_floor_f32_e32 v68, v68
	v_fma_f32 v68, v143, v145, -v68
	v_sin_f32_e32 v110, v68
	v_cos_f32_e32 v111, v68
	v_add_u32_e32 v68, 16, v78
	v_mul_f32_e32 v144, 0.15915494, v0
	v_cvt_f32_i32_e32 v68, v68
	v_mul_f32_e32 v0, v144, v145
	v_floor_f32_e32 v0, v0
	v_fma_f32 v0, v144, v145, -v0
	v_sin_f32_e32 v99, v0
	v_cos_f32_e32 v98, v0
	v_mul_f32_e32 v0, 0xbed49a78, v68
	s_waitcnt vmcnt(5)
; __device__ __forceinline__ float bflo(unsigned w) { return __uint_as_float(w << 16); }
; __device__ __forceinline__ float bfhi(unsigned w) { return __uint_as_float(w & 0xffff0000u); }
; __device__ __forceinline__ void attn_item(const bf16_t* __restrict__ Qb, const bf16_t* __restrict__ Kh, const bf16_t* __restrict__ Vh, const bf16_t* __restrict__ Zb, ...
;     ...
;     for (int d0 = 0; d0 < 8; ++d0) qw[d0] = *reinterpret_cast<const u32x4*>(Qw + d0 * 16);
;     float ss = 0.f;
; #pragma unroll
;     for (int d0 = 0; d0 < 8; ++d0) { const float a0 = bflo(qw[d0].x), a1 = bfhi(qw[d0].x), a2 = bflo(qw[d0].y), a3 = bfhi(qw[d0].y), a4 = bflo(qw[d0].z), a5 = bfhi(qw[d0].z), a6 = bflo(qw[d0].w), a7 = bfhi(qw[d0].w);
;       ss += (a0 * a0 + a1 * a1) + (a2 * a2 + a3 * a3) + (a4 * a4 + a5 * a5) + (a6 * a6 + a7 * a7); }
;     { auto rr = __builtin_amdgcn_permlane32_swap(__float_as_uint(ss), __float_as_uint(ss), false, false); ss = __uint_as_float(rr[0]) + __uint_as_float(rr[1]); }
	v_lshlrev_b32_e32 v93, 16, v57
	v_and_b32_e32 v91, 0xffff0000, v57
	v_and_b32_e32 v155, 0xffff0000, v43
	v_and_b32_e32 v157, 0xffff0000, v42
	v_exp_f32_e32 v79, v0
	v_mov_b32_e32 v94, v93
	v_mov_b32_e32 v95, v91
	v_mul_f32_e32 v0, v91, v91
	v_lshlrev_b32_e32 v113, 16, v49
	v_and_b32_e32 v123, 0xffff0000, v49
	v_lshlrev_b32_e32 v57, 16, v43
	v_lshlrev_b32_e32 v49, 16, v42
	v_mov_b32_e32 v42, v155
	v_mov_b32_e32 v43, v157
	v_pk_fma_f32 v[150:151], v[94:95], v[94:95], v[0:1] op_sel_hi:[1,1,0]
	v_lshlrev_b32_e32 v103, 16, v56
	v_and_b32_e32 v95, 0xffff0000, v56
	v_lshlrev_b32_e32 v125, 16, v48
	v_and_b32_e32 v117, 0xffff0000, v48
	v_lshlrev_b32_e32 v56, 16, v39
	v_and_b32_e32 v154, 0xffff0000, v39
	v_lshlrev_b32_e32 v48, 16, v38
	v_and_b32_e32 v156, 0xffff0000, v38
	v_mov_b32_e32 v38, v57
	v_mov_b32_e32 v39, v49
	v_pk_mul_f32 v[42:43], v[42:43], v[42:43]
	v_and_b32_e32 v159, 0xffff0000, v41
	v_pk_fma_f32 v[38:39], v[38:39], v[38:39], v[42:43]
	v_lshlrev_b32_e32 v43, 16, v41
	v_and_b32_e32 v41, 0xffff0000, v40
	v_and_b32_e32 v118, 0xffff0000, v47
	v_lshlrev_b32_e32 v161, 16, v40
	v_mov_b32_e32 v162, v41
	v_mov_b32_e32 v163, v159
	v_and_b32_e32 v70, 0xffff0000, v63
	v_lshlrev_b32_e32 v72, 16, v62
	v_and_b32_e32 v62, 0xffff0000, v62
	v_lshlrev_b32_e32 v114, 16, v47
	v_and_b32_e32 v120, 0xffff0000, v46
	v_lshlrev_b32_e32 v42, 16, v37
	v_and_b32_e32 v158, 0xffff0000, v37
	v_lshlrev_b32_e32 v160, 16, v36
	v_and_b32_e32 v40, 0xffff0000, v36
	v_mov_b32_e32 v36, v161
	v_mov_b32_e32 v37, v43
	v_pk_mul_f32 v[162:163], v[162:163], v[162:163]
	v_mov_b32_e32 v164, v154
	v_mov_b32_e32 v165, v118
	v_lshlrev_b32_e32 v68, 16, v63
	v_mov_b32_e32 v74, v70
	v_mov_b32_e32 v75, v62
	v_lshlrev_b32_e32 v126, 16, v46
	v_and_b32_e32 v122, 0xffff0000, v45
	v_pk_fma_f32 v[36:37], v[36:37], v[36:37], v[162:163]
	v_mov_b32_e32 v162, v56
	v_mov_b32_e32 v163, v114
	v_pk_mul_f32 v[164:165], v[164:165], v[164:165]
	v_mov_b32_e32 v166, v156
	v_mov_b32_e32 v167, v120
	s_waitcnt vmcnt(4)
	v_lshlrev_b32_e32 v69, 16, v67
	v_and_b32_e32 v71, 0xffff0000, v67
	v_lshlrev_b32_e32 v73, 16, v66
	v_and_b32_e32 v63, 0xffff0000, v66
	v_mov_b32_e32 v66, v68
	v_mov_b32_e32 v67, v72
	v_pk_mul_f32 v[74:75], v[74:75], v[74:75]
	v_lshlrev_b32_e32 v112, 16, v45
	v_and_b32_e32 v116, 0xffff0000, v44
	v_pk_fma_f32 v[162:163], v[162:163], v[162:163], v[164:165]
	v_mov_b32_e32 v164, v48
	v_mov_b32_e32 v165, v126
	v_pk_mul_f32 v[166:167], v[166:167], v[166:167]
	v_mov_b32_e32 v168, v158
	v_mov_b32_e32 v169, v122
	v_pk_fma_f32 v[80:81], v[66:67], v[66:67], v[74:75]
	v_and_b32_e32 v66, 0xffff0000, v61
	v_lshlrev_b32_e32 v76, 16, v60
	v_and_b32_e32 v60, 0xffff0000, v60
	v_lshlrev_b32_e32 v124, 16, v44
	v_pk_fma_f32 v[164:165], v[164:165], v[164:165], v[166:167]
	v_mov_b32_e32 v166, v42
	v_mov_b32_e32 v167, v112
	v_pk_mul_f32 v[168:169], v[168:169], v[168:169]
	v_mov_b32_e32 v170, v40
	v_mov_b32_e32 v171, v116
	v_lshlrev_b32_e32 v74, 16, v61
	v_mov_b32_e32 v84, v60
	v_mov_b32_e32 v85, v66
	v_pk_fma_f32 v[166:167], v[166:167], v[166:167], v[168:169]
	v_mov_b32_e32 v168, v160
	v_mov_b32_e32 v169, v124
	v_pk_mul_f32 v[170:171], v[170:171], v[170:171]
	v_lshlrev_b32_e32 v75, 16, v65
	v_and_b32_e32 v67, 0xffff0000, v65
	v_lshlrev_b32_e32 v77, 16, v64
	v_and_b32_e32 v61, 0xffff0000, v64
	v_mov_b32_e32 v64, v76
	v_mov_b32_e32 v65, v74
	v_pk_mul_f32 v[84:85], v[84:85], v[84:85]
	v_pk_fma_f32 v[168:169], v[168:169], v[168:169], v[170:171]
	v_pk_fma_f32 v[64:65], v[64:65], v[64:65], v[84:85]
	v_lshlrev_b32_e32 v92, 16, v53
	v_and_b32_e32 v90, 0xffff0000, v53
	v_lshlrev_b32_e32 v102, 16, v52
	v_and_b32_e32 v94, 0xffff0000, v52
	v_mov_b32_e32 v52, v103
	v_mov_b32_e32 v53, v95
	v_mul_f32_e32 v0, v95, v95
	v_pk_add_f32 v[166:167], v[168:169], v[166:167]
	v_pk_add_f32 v[64:65], v[64:65], v[64:65] op_sel:[0,1] op_sel_hi:[1,0]
	v_and_b32_e32 v87, 0xffff0000, v58
	v_and_b32_e32 v86, 0xffff0000, v54
	v_pk_fma_f32 v[52:53], v[52:53], v[52:53], v[0:1] op_sel_hi:[1,1,0]
	v_and_b32_e32 v119, 0xffff0000, v51
	v_mov_b32_e32 v46, v113
	v_mov_b32_e32 v47, v123
	v_mul_f32_e32 v0, v123, v123
	v_pk_add_f32 v[36:37], v[36:37], v[36:37] op_sel:[0,1] op_sel_hi:[1,0]
	v_pk_add_f32 v[164:165], v[164:165], v[166:167]
	v_pk_add_f32 v[64:65], v[80:81], v[64:65] op_sel:[1,0] op_sel_hi:[0,1]
	v_lshlrev_b32_e32 v89, 16, v58
	v_lshlrev_b32_e32 v88, 16, v54
	v_lshlrev_b32_e32 v115, 16, v51
	v_and_b32_e32 v121, 0xffff0000, v50
	v_pk_fma_f32 v[46:47], v[46:47], v[46:47], v[0:1] op_sel_hi:[1,1,0]
	v_mov_b32_e32 v44, v125
	v_mov_b32_e32 v45, v117
	v_mul_f32_e32 v0, v117, v117
	v_pk_add_f32 v[36:37], v[38:39], v[36:37] op_sel:[1,0] op_sel_hi:[0,1]
	v_pk_add_f32 v[162:163], v[162:163], v[164:165]
	v_pk_mov_b32 v[164:165], v[118:119], v[86:87] op_sel:[1,0]
	v_pk_add_f32 v[64:65], v[80:81], v[64:65]
	v_lshlrev_b32_e32 v85, 16, v59
	v_lshlrev_b32_e32 v84, 16, v55
	v_and_b32_e32 v81, 0xffff0000, v59
	v_and_b32_e32 v80, 0xffff0000, v55
	v_pk_mul_f32 v[54:55], v[92:93], v[92:93]
	v_pk_mul_f32 v[58:59], v[90:91], v[90:91]
	v_lshlrev_b32_e32 v127, 16, v50
	v_pk_fma_f32 v[44:45], v[44:45], v[44:45], v[0:1] op_sel_hi:[1,1,0]
	v_pk_add_f32 v[36:37], v[38:39], v[36:37]
	v_pk_add_f32 v[38:39], v[162:163], v[162:163] op_sel:[0,1] op_sel_hi:[1,0]
	v_pk_mov_b32 v[162:163], v[114:115], v[88:89] op_sel:[1,0]
	v_pk_mul_f32 v[164:165], v[164:165], v[164:165]
	v_pk_mov_b32 v[166:167], v[120:121], v[94:95] op_sel:[1,0]
	v_pk_fma_f32 v[162:163], v[162:163], v[162:163], v[164:165]
	v_pk_mov_b32 v[164:165], v[126:127], v[102:103] op_sel:[1,0]
	v_pk_mul_f32 v[166:167], v[166:167], v[166:167]
	v_mov_b32_e32 v45, v54
	v_mov_b32_e32 v47, v58
	v_pk_mul_f32 v[146:147], v[84:85], v[84:85]
	v_pk_mul_f32 v[148:149], v[80:81], v[80:81]
	v_pk_fma_f32 v[164:165], v[164:165], v[164:165], v[166:167]
	v_pk_add_f32 v[44:45], v[44:45], v[46:47]
	v_mov_b32_e32 v39, v146
	v_pk_add_f32 v[44:45], v[164:165], v[44:45]
	v_mov_b32_e32 v37, v148
	v_pk_add_f32 v[44:45], v[162:163], v[44:45]
	v_pk_add_f32 v[36:37], v[38:39], v[36:37]
	v_pk_mul_f32 v[132:133], v[74:75], v[74:75]
	v_pk_add_f32 v[36:37], v[36:37], v[44:45]
	v_mov_b32_e32 v44, v81
	v_mov_b32_e32 v45, v63
	v_pk_mul_f32 v[134:135], v[66:67], v[66:67]
	v_mov_b32_e32 v38, v85
	v_mov_b32_e32 v39, v73
	v_pk_mul_f32 v[44:45], v[44:45], v[44:45]
	v_mov_b32_e32 v46, v87
	v_mov_b32_e32 v47, v61
	v_pk_fma_f32 v[38:39], v[38:39], v[38:39], v[44:45]
	v_mov_b32_e32 v44, v89
	v_mov_b32_e32 v45, v77
	v_pk_mul_f32 v[46:47], v[46:47], v[46:47]
	v_mov_b32_e32 v53, v133
	v_mov_b32_e32 v151, v135
	v_pk_mul_f32 v[128:129], v[68:69], v[68:69]
	v_pk_mul_f32 v[130:131], v[70:71], v[70:71]
	v_pk_add_f32 v[36:37], v[36:37], v[36:37] op_sel:[0,1] op_sel_hi:[1,0]
	v_pk_fma_f32 v[44:45], v[44:45], v[44:45], v[46:47]
	v_pk_add_f32 v[46:47], v[52:53], v[150:151]
	v_mov_b32_e32 v37, v129
	v_pk_add_f32 v[44:45], v[44:45], v[46:47]
	v_mov_b32_e32 v65, v131
	v_pk_add_f32 v[38:39], v[38:39], v[44:45]
	v_pk_add_f32 v[36:37], v[36:37], v[64:65]
	s_waitcnt vmcnt(2)
; __device__ __forceinline__ int lane_id_asm() { int r; asm volatile("v_mbcnt_lo_u32_b32 %0, -1, 0\n\tv_mbcnt_hi_u32_b32 %0, -1, %0" : "=v"(r)); return r; }
; __device__ __forceinline__ float bflo(unsigned w) { return __uint_as_float(w << 16); }
; __device__ __forceinline__ void attn_item(const bf16_t* __restrict__ Qb, const bf16_t* __restrict__ Kh, const bf16_t* __restrict__ Vh, const bf16_t* __restrict__ Zb, ...
;     ...
;     { auto rr = __builtin_amdgcn_permlane32_swap(__float_as_uint(ss), __float_as_uint(ss), false, false); ss = __uint_as_float(rr[0]) + __uint_as_float(rr[1]); }
;     const float rstd = __builtin_amdgcn_rsqf(ss * (1.0f / 128.0f) + NORM_EPS) * (SCALE * 1.4426950408889634f);
;     const int hq = lane_id_asm() >> 5;
;     const int spos = qpos0 + wid * QBLK + r32; const float prow = (float)(spos >> 6), pcol = (float)(spos & 63);
; #pragma unroll
;     for (int bb = 0; bb < 4; ++bb) { const int d1 = (bb & 1) + 4 * (bb >> 1), d2 = d1 + 2;
;       const float pos = (bb < 2) ? prow : pcol; const float* g1p = qg + d1 * 16 + hq * 8; const float* g2p = qg + d2 * 16 + hq * 8;
;       const f32x4 g1a = *(const f32x4*)g1p, g1b = *(const f32x4*)(g1p + 4), g2a = *(const f32x4*)g2p, g2b = *(const f32x4*)(g2p + 4);
;       float o1[8], o2[8];
; #pragma unroll
;       for (int e = 0; e < 8; ++e) { const unsigned w1 = (e < 2) ? qw[d1].x : (e < 4) ? qw[d1].y : (e < 6) ? qw[d1].z : qw[d1].w, w2 = (e < 2) ? qw[d2].x : (e < 4) ? qw[d2].y : (e < 6) ? qw[d2].z : qw[d2].w;
;         const float x1 = (e & 1) ? bfhi(w1) : bflo(w1), x2 = (e & 1) ? bfhi(w2) : bflo(w2); const float ga = (e < 4) ? g1a[e & 3] : g1b[e & 3], gb = (e < 4) ? g2a[e & 3] : g2b[e & 3];
;         const int fi = (d1 & 1) * 16 + hq * 8 + e; float rev = pos * (__builtin_amdgcn_exp2f(-(float)fi * (13.287712379549449f / 32.0f)) * 0.15915494309189535f); rev -= floorf(rev);
;         const float sn = sin_rev(rev), cs = cos_rev(rev), y1 = x1 * rstd * ga, y2 = x2 * rstd * gb; o1[e] = y1 * cs - y2 * sn; o2[e] = y2 * cs + y1 * sn; }
; #pragma unroll
;       for (int e = 0; e < 8; ++e) qn2 += o1[e] * o1[e] + o2[e] * o2[e];
;       u32x4 p1 = {cvtpk(o1[0], o1[1]), cvtpk(o1[2], o1[3]), cvtpk(o1[4], o1[5]), cvtpk(o1[6], o1[7])}, p2 = {cvtpk(o2[0], o2[1]), cvtpk(o2[2], o2[3]), cvtpk(o2[4], o2[5]), cvtpk(o2[6], o2[7])};
;       qr[d1] = *reinterpret_cast<bf16x8*>(&p1); qr[d2] = *reinterpret_cast<bf16x8*>(&p2); }
	v_mov_b32_e32 v50, v2
	v_pk_add_f32 v[36:37], v[36:37], v[38:39]
	v_mov_b32_e32 v128, v12
	v_pk_add_f32 v[36:37], v[36:37], v[36:37] op_sel:[0,1] op_sel_hi:[1,0]
	s_waitcnt vmcnt(1)
	v_mov_b32_e32 v129, v34
	v_mov_b32_e32 v0, v36
	s_nop 1
	v_permlane32_swap_b32_e32 v36, v0
	v_add_f32_e32 v0, v36, v0
	v_fmamk_f32 v0, v0, 0x3c000000, v217
	v_rsq_f32_e32 v0, v0
	v_mov_b32_e32 v36, v10
	v_mov_b32_e32 v37, v32
	v_mov_b32_e32 v32, v11
	v_mul_f32_e32 v0, 0x3e0293ee, v0
	v_pk_mul_f32 v[38:39], v[0:1], v[160:161] op_sel_hi:[0,1]
	v_pk_mul_f32 v[38:39], v[36:37], v[38:39]
	v_mov_b32_e32 v36, v105
	v_mov_b32_e32 v37, v104
	v_mul_f32_e32 v2, v39, v104
	v_pk_mul_f32 v[40:41], v[0:1], v[40:41] op_sel_hi:[0,1]
	v_pk_fma_f32 v[36:37], v[38:39], v[36:37], v[2:3] op_sel_hi:[1,1,0] neg_lo:[0,0,1] neg_hi:[0,0,1]
	v_mul_f32_e32 v2, v39, v105
	v_pk_mul_f32 v[10:11], v[32:33], v[40:41]
	v_pk_fma_f32 v[38:39], v[38:39], v[104:105], v[2:3] op_sel_hi:[1,1,0]
	v_mul_f32_e32 v2, v11, v83
	v_pk_fma_f32 v[32:33], v[10:11], v[82:83], v[2:3] op_sel_hi:[1,1,0] neg_lo:[0,0,1] neg_hi:[0,0,1]
	v_mov_b32_e32 v40, v83
	v_mov_b32_e32 v41, v82
	v_mul_f32_e32 v2, v11, v82
	v_pk_fma_f32 v[40:41], v[10:11], v[40:41], v[2:3] op_sel_hi:[1,1,0]
	v_pk_mul_f32 v[10:11], v[0:1], v[42:43] op_sel_hi:[0,1]
	v_pk_mul_f32 v[10:11], v[128:129], v[10:11]
	v_mov_b32_e32 v42, v107
	v_mov_b32_e32 v43, v106
	v_mul_f32_e32 v2, v11, v106
	v_pk_fma_f32 v[42:43], v[10:11], v[42:43], v[2:3] op_sel_hi:[1,1,0] neg_lo:[0,0,1] neg_hi:[0,0,1]
	v_mul_f32_e32 v2, v11, v107
	v_pk_fma_f32 v[44:45], v[10:11], v[106:107], v[2:3] op_sel_hi:[1,1,0]
	v_pk_mul_f32 v[10:11], v[0:1], v[158:159] op_sel_hi:[0,1]
	v_mov_b32_e32 v34, v13
	v_pk_mul_f32 v[10:11], v[34:35], v[10:11]
	v_mov_b32_e32 v12, v97
	v_mul_f32_e32 v2, v11, v97
	v_pk_fma_f32 v[34:35], v[10:11], v[96:97], v[2:3] op_sel_hi:[1,1,0] neg_lo:[0,0,1] neg_hi:[0,0,1]
	v_mov_b32_e32 v13, v96
	v_mul_f32_e32 v2, v11, v96
	s_waitcnt vmcnt(0)
	v_mov_b32_e32 v51, v6
	v_pk_fma_f32 v[46:47], v[10:11], v[12:13], v[2:3] op_sel_hi:[1,1,0]
	v_pk_mul_f32 v[10:11], v[0:1], v[48:49] op_sel_hi:[0,1]
	v_pk_mul_f32 v[10:11], v[50:51], v[10:11]
	v_mov_b32_e32 v12, v109
	v_mov_b32_e32 v13, v108
	v_mul_f32_e32 v2, v11, v108
	v_pk_fma_f32 v[48:49], v[10:11], v[12:13], v[2:3] op_sel_hi:[1,1,0] neg_lo:[0,0,1] neg_hi:[0,0,1]
	v_mul_f32_e32 v2, v11, v109
	v_pk_fma_f32 v[50:51], v[10:11], v[108:109], v[2:3] op_sel_hi:[1,1,0]
	v_pk_mul_f32 v[10:11], v[0:1], v[156:157] op_sel_hi:[0,1]
	v_mov_b32_e32 v6, v3
	v_pk_mul_f32 v[2:3], v[6:7], v[10:11]
	v_mov_b32_e32 v152, v4
	v_mul_f32_e32 v4, v3, v101
	v_pk_fma_f32 v[52:53], v[2:3], v[100:101], v[4:5] op_sel_hi:[1,1,0] neg_lo:[0,0,1] neg_hi:[0,0,1]
	v_mov_b32_e32 v6, v101
	v_mov_b32_e32 v7, v100
	v_mul_f32_e32 v4, v3, v100
	v_mov_b32_e32 v153, v8
	v_pk_fma_f32 v[54:55], v[2:3], v[6:7], v[4:5] op_sel_hi:[1,1,0]
	v_pk_mul_f32 v[2:3], v[0:1], v[56:57] op_sel_hi:[0,1]
	v_pk_mul_f32 v[2:3], v[152:153], v[2:3]
	v_mov_b32_e32 v6, v111
	v_mov_b32_e32 v7, v110
	v_mul_f32_e32 v4, v3, v110
	v_pk_fma_f32 v[56:57], v[2:3], v[6:7], v[4:5] op_sel_hi:[1,1,0] neg_lo:[0,0,1] neg_hi:[0,0,1]
	v_mul_f32_e32 v4, v3, v111
	v_pk_fma_f32 v[58:59], v[2:3], v[110:111], v[4:5] op_sel_hi:[1,1,0]
	v_pk_mul_f32 v[2:3], v[0:1], v[154:155] op_sel_hi:[0,1]
	v_mov_b32_e32 v8, v5
	v_pk_mul_f32 v[2:3], v[8:9], v[2:3]
	v_cvt_pk_bf16_f32 v152, v36, v32
	v_cvt_pk_bf16_f32 v153, v42, v34
	v_cvt_pk_bf16_f32 v154, v48, v52
	v_add_u32_e32 v96, 17, v78
	v_mul_f32_e32 v4, v3, v99
	v_pk_fma_f32 v[64:65], v[2:3], v[98:99], v[4:5] op_sel_hi:[1,1,0] neg_lo:[0,0,1] neg_hi:[0,0,1]
	v_mov_b32_e32 v4, v99
	v_mov_b32_e32 v5, v98
	v_mul_f32_e32 v6, v3, v98
	v_pk_fma_f32 v[82:83], v[2:3], v[4:5], v[6:7] op_sel_hi:[1,1,0]
	v_cvt_pk_bf16_f32 v155, v56, v64
	v_cvt_pk_bf16_f32 v148, v38, v40
	v_cvt_pk_bf16_f32 v149, v44, v46
	v_cvt_pk_bf16_f32 v150, v50, v54
	v_cvt_f32_i32_e32 v96, v96
	v_cvt_pk_bf16_f32 v151, v58, v82
	global_load_dwordx4 v[2:5], v[14:15], off offset:80
	global_load_dwordx4 v[6:9], v[14:15], off offset:64
	global_load_dwordx4 v[10:13], v[14:15], off offset:192
	global_load_dwordx4 v[128:131], v[14:15], off offset:208
	v_mul_f32_e32 v176, 0.15915494, v79
	v_mul_f32_e32 v96, 0xbed49a78, v96
	v_exp_f32_e32 v98, v96
	v_mul_f32_e32 v79, v176, v145
	v_floor_f32_e32 v79, v79
	v_fma_f32 v79, v176, v145, -v79
	v_mul_f32_e32 v177, 0.15915494, v98
	v_add_u32_e32 v98, 18, v78
	v_cvt_f32_i32_e32 v98, v98
	v_sin_f32_e32 v96, v79
	v_cos_f32_e32 v97, v79
	v_mul_f32_e32 v79, v177, v145
	v_floor_f32_e32 v79, v79
	v_fma_f32 v79, v177, v145, -v79
	v_mul_f32_e32 v98, 0xbed49a78, v98
	v_sin_f32_e32 v99, v79
	v_exp_f32_e32 v100, v98
	v_cos_f32_e32 v98, v79
	v_add_u32_e32 v79, 19, v78
	v_cvt_f32_i32_e32 v79, v79
	v_add_u32_e32 v104, 20, v78
	v_cvt_f32_i32_e32 v104, v104
	v_mul_f32_e32 v178, 0.15915494, v100
	v_mul_f32_e32 v79, 0xbed49a78, v79
	v_exp_f32_e32 v79, v79
	v_mul_f32_e32 v104, 0xbed49a78, v104
	v_exp_f32_e32 v104, v104
	v_mul_f32_e32 v100, v178, v145
	v_mul_f32_e32 v179, 0.15915494, v79
	v_mul_f32_e32 v79, v179, v145
	v_floor_f32_e32 v79, v79
	v_fma_f32 v79, v179, v145, -v79
	v_mul_f32_e32 v180, 0.15915494, v104
	v_sin_f32_e32 v107, v79
	v_cos_f32_e32 v106, v79
	v_add_u32_e32 v79, 21, v78
	v_mul_f32_e32 v104, v180, v145
	v_cvt_f32_i32_e32 v79, v79
	v_floor_f32_e32 v104, v104
	v_fma_f32 v104, v180, v145, -v104
	v_sin_f32_e32 v110, v104
	v_cos_f32_e32 v111, v104
	v_add_u32_e32 v104, 22, v78
	v_add_u32_e32 v78, 23, v78
	v_cvt_f32_i32_e32 v104, v104
	v_cvt_f32_i32_e32 v78, v78
	v_mul_f32_e32 v79, 0xbed49a78, v79
	v_exp_f32_e32 v79, v79
	v_mul_f32_e32 v104, 0xbed49a78, v104
	v_mul_f32_e32 v78, 0xbed49a78, v78
	v_exp_f32_e32 v104, v104
	v_exp_f32_e32 v78, v78
	v_mul_f32_e32 v181, 0.15915494, v79
	v_mul_f32_e32 v79, v181, v145
	v_floor_f32_e32 v79, v79
	v_fma_f32 v79, v181, v145, -v79
	v_mul_f32_e32 v182, 0.15915494, v104
	v_mul_f32_e32 v183, 0.15915494, v78
	v_sin_f32_e32 v133, v79
	v_cos_f32_e32 v132, v79
	v_mul_f32_e32 v79, v182, v145
	v_mul_f32_e32 v78, v183, v145
	v_floor_f32_e32 v79, v79
	v_floor_f32_e32 v78, v78
	v_fma_f32 v79, v182, v145, -v79
	v_fma_f32 v78, v183, v145, -v78
	v_sin_f32_e32 v134, v79
	v_cos_f32_e32 v135, v79
	v_sin_f32_e32 v147, v78
	v_cos_f32_e32 v146, v78
	v_pk_mul_f32 v[78:79], v[0:1], v[124:125] op_sel_hi:[0,1]
	v_floor_f32_e32 v100, v100
	v_fma_f32 v101, v178, v145, -v100
	v_sin_f32_e32 v100, v101
	v_cos_f32_e32 v101, v101
	v_pk_mul_f32 v[102:103], v[0:1], v[102:103] op_sel_hi:[0,1]
	v_pk_mul_f32 v[94:95], v[0:1], v[94:95] op_sel_hi:[0,1]
	s_waitcnt vmcnt(2)
; __device__ __forceinline__ unsigned cvtpk(float lo, float hi) { unsigned r; asm volatile("v_cvt_pk_bf16_f32 %0, %1, %2" : "=v"(r) : "v"(lo), "v"(hi)); return r; }
; __device__ __forceinline__ float bflo(unsigned w) { return __uint_as_float(w << 16); }
; __device__ __forceinline__ float bfhi(unsigned w) { return __uint_as_float(w & 0xffff0000u); }
; __device__ __forceinline__ float sin_rev(float rev) { return __builtin_amdgcn_sinf(rev); }
; __device__ __forceinline__ float cos_rev(float rev) { return __builtin_amdgcn_cosf(rev); }
; __device__ __forceinline__ void attn_item(const bf16_t* __restrict__ Qb, const bf16_t* __restrict__ Kh, const bf16_t* __restrict__ Vh, const bf16_t* __restrict__ Zb, ...
;     ...
;     for (int bb = 0; bb < 4; ++bb) { const int d1 = (bb & 1) + 4 * (bb >> 1), d2 = d1 + 2;
;       const float pos = (bb < 2) ? prow : pcol; const float* g1p = qg + d1 * 16 + hq * 8; const float* g2p = qg + d2 * 16 + hq * 8;
;       const f32x4 g1a = *(const f32x4*)g1p, g1b = *(const f32x4*)(g1p + 4), g2a = *(const f32x4*)g2p, g2b = *(const f32x4*)(g2p + 4);
;       float o1[8], o2[8];
; #pragma unroll
;       for (int e = 0; e < 8; ++e) { const unsigned w1 = (e < 2) ? qw[d1].x : (e < 4) ? qw[d1].y : (e < 6) ? qw[d1].z : qw[d1].w, w2 = (e < 2) ? qw[d2].x : (e < 4) ? qw[d2].y : (e < 6) ? qw[d2].z : qw[d2].w;
;         const float x1 = (e & 1) ? bfhi(w1) : bflo(w1), x2 = (e & 1) ? bfhi(w2) : bflo(w2); const float ga = (e < 4) ? g1a[e & 3] : g1b[e & 3], gb = (e < 4) ? g2a[e & 3] : g2b[e & 3];
;         const int fi = (d1 & 1) * 16 + hq * 8 + e; float rev = pos * (__builtin_amdgcn_exp2f(-(float)fi * (13.287712379549449f / 32.0f)) * 0.15915494309189535f); rev -= floorf(rev);
;         const float sn = sin_rev(rev), cs = cos_rev(rev), y1 = x1 * rstd * ga, y2 = x2 * rstd * gb; o1[e] = y1 * cs - y2 * sn; o2[e] = y2 * cs + y1 * sn; }
; #pragma unroll
;       for (int e = 0; e < 8; ++e) qn2 += o1[e] * o1[e] + o2[e] * o2[e];
;       u32x4 p1 = {cvtpk(o1[0], o1[1]), cvtpk(o1[2], o1[3]), cvtpk(o1[4], o1[5]), cvtpk(o1[6], o1[7])}, p2 = {cvtpk(o2[0], o2[1]), cvtpk(o2[2], o2[3]), cvtpk(o2[4], o2[5]), cvtpk(o2[6], o2[7])};
;       qr[d1] = *reinterpret_cast<bf16x8*>(&p1); qr[d2] = *reinterpret_cast<bf16x8*>(&p2); }
	v_mov_b32_e32 v104, v6
	s_waitcnt vmcnt(1)
	v_mov_b32_e32 v105, v10
	v_pk_mul_f32 v[104:105], v[78:79], v[104:105]
	v_mov_b32_e32 v78, v97
	v_mov_b32_e32 v79, v96
	v_mul_f32_e32 v6, v96, v105
	v_pk_fma_f32 v[78:79], v[78:79], v[104:105], v[6:7] op_sel_hi:[1,1,0] neg_lo:[0,0,1] neg_hi:[0,0,1]
	v_mul_f32_e32 v6, v97, v105
	v_pk_fma_f32 v[96:97], v[96:97], v[104:105], v[6:7] op_sel_hi:[1,1,0]
	v_pk_mul_f32 v[104:105], v[0:1], v[116:117] op_sel_hi:[0,1]
	v_mov_b32_e32 v10, v7
	v_pk_mul_f32 v[6:7], v[104:105], v[10:11]
	v_pk_mul_f32 v[76:77], v[0:1], v[76:77] op_sel_hi:[0,1]
	v_mul_f32_e32 v10, v99, v7
	v_pk_fma_f32 v[104:105], v[98:99], v[6:7], v[10:11] op_sel_hi:[1,1,0] neg_lo:[0,0,1] neg_hi:[0,0,1]
	v_mov_b32_e32 v10, v99
	v_mov_b32_e32 v11, v98
	v_mul_f32_e32 v98, v98, v7
	v_pk_fma_f32 v[108:109], v[10:11], v[6:7], v[98:99] op_sel_hi:[1,1,0]
	v_pk_mul_f32 v[6:7], v[0:1], v[112:113] op_sel_hi:[0,1]
	v_mov_b32_e32 v10, v8
	v_mov_b32_e32 v11, v12
	v_pk_mul_f32 v[6:7], v[6:7], v[10:11]
	v_mov_b32_e32 v10, v101
	v_mov_b32_e32 v11, v100
	v_mul_f32_e32 v8, v100, v7
	v_pk_fma_f32 v[112:113], v[10:11], v[6:7], v[8:9] op_sel_hi:[1,1,0] neg_lo:[0,0,1] neg_hi:[0,0,1]
	v_mul_f32_e32 v8, v101, v7
	v_pk_fma_f32 v[116:117], v[100:101], v[6:7], v[8:9] op_sel_hi:[1,1,0]
	v_pk_mul_f32 v[6:7], v[0:1], v[122:123] op_sel_hi:[0,1]
	v_mov_b32_e32 v12, v9
	v_pk_mul_f32 v[6:7], v[6:7], v[12:13]
	v_cvt_pk_bf16_f32 v160, v78, v104
	s_mulk_i32 s0, 0x2080
	v_mul_f32_e32 v8, v107, v7
	v_pk_fma_f32 v[122:123], v[106:107], v[6:7], v[8:9] op_sel_hi:[1,1,0] neg_lo:[0,0,1] neg_hi:[0,0,1]
	v_mov_b32_e32 v8, v107
	v_mov_b32_e32 v9, v106
	v_mul_f32_e32 v10, v106, v7
	v_pk_fma_f32 v[124:125], v[8:9], v[6:7], v[10:11] op_sel_hi:[1,1,0]
	v_pk_mul_f32 v[6:7], v[0:1], v[126:127] op_sel_hi:[0,1]
	v_mov_b32_e32 v8, v2
	s_waitcnt vmcnt(0)
	v_mov_b32_e32 v9, v128
	v_pk_mul_f32 v[6:7], v[6:7], v[8:9]
	v_mov_b32_e32 v8, v111
	v_mov_b32_e32 v9, v110
	v_mul_f32_e32 v2, v110, v7
	v_pk_fma_f32 v[98:99], v[8:9], v[6:7], v[2:3] op_sel_hi:[1,1,0] neg_lo:[0,0,1] neg_hi:[0,0,1]
	v_mul_f32_e32 v2, v111, v7
	v_pk_fma_f32 v[100:101], v[110:111], v[6:7], v[2:3] op_sel_hi:[1,1,0]
	v_pk_mul_f32 v[6:7], v[0:1], v[120:121] op_sel_hi:[0,1]
	v_mov_b32_e32 v128, v3
	v_pk_mul_f32 v[2:3], v[6:7], v[128:129]
	v_cvt_pk_bf16_f32 v161, v112, v122
	v_and_b32_e32 v128, 63, v136
	v_mul_f32_e32 v6, v133, v3
	v_pk_fma_f32 v[106:107], v[132:133], v[2:3], v[6:7] op_sel_hi:[1,1,0] neg_lo:[0,0,1] neg_hi:[0,0,1]
	v_mov_b32_e32 v6, v133
	v_mov_b32_e32 v7, v132
	v_mul_f32_e32 v8, v132, v3
	v_pk_fma_f32 v[110:111], v[6:7], v[2:3], v[8:9] op_sel_hi:[1,1,0]
	v_pk_mul_f32 v[2:3], v[0:1], v[114:115] op_sel_hi:[0,1]
	v_mov_b32_e32 v6, v4
	v_mov_b32_e32 v7, v130
	v_pk_mul_f32 v[2:3], v[2:3], v[6:7]
	v_mov_b32_e32 v6, v135
	v_mov_b32_e32 v7, v134
	v_mul_f32_e32 v4, v134, v3
	v_pk_fma_f32 v[114:115], v[6:7], v[2:3], v[4:5] op_sel_hi:[1,1,0] neg_lo:[0,0,1] neg_hi:[0,0,1]
	v_mul_f32_e32 v4, v135, v3
	v_pk_fma_f32 v[120:121], v[134:135], v[2:3], v[4:5] op_sel_hi:[1,1,0]
	v_pk_mul_f32 v[2:3], v[0:1], v[118:119] op_sel_hi:[0,1]
	v_mov_b32_e32 v130, v5
	v_pk_mul_f32 v[2:3], v[2:3], v[130:131]
	v_cvt_pk_bf16_f32 v162, v98, v106
	v_cvt_f32_ubyte0_e32 v189, v128
	v_mul_f32_e32 v4, v147, v3
	v_pk_fma_f32 v[118:119], v[146:147], v[2:3], v[4:5] op_sel_hi:[1,1,0] neg_lo:[0,0,1] neg_hi:[0,0,1]
	v_mov_b32_e32 v4, v147
	v_mov_b32_e32 v5, v146
	v_mul_f32_e32 v6, v146, v3
	v_pk_fma_f32 v[126:127], v[4:5], v[2:3], v[6:7] op_sel_hi:[1,1,0]
	v_cvt_pk_bf16_f32 v163, v114, v118
	v_cvt_pk_bf16_f32 v156, v96, v108
	v_cvt_pk_bf16_f32 v157, v116, v124
	v_cvt_pk_bf16_f32 v158, v100, v110
	v_mul_f32_e32 v130, v138, v189
	v_cvt_pk_bf16_f32 v159, v120, v126
	global_load_dwordx4 v[2:5], v[14:15], off offset:256
	global_load_dwordx4 v[6:9], v[14:15], off offset:384
	global_load_dwordx4 v[10:13], v[14:15], off offset:272
	global_load_dwordx4 v[164:167], v[14:15], off offset:400
	v_mul_f32_e32 v128, v137, v189
	v_floor_f32_e32 v130, v130
	v_floor_f32_e32 v128, v128
	v_fma_f32 v130, v138, v189, -v130
	v_mul_f32_e32 v138, v142, v189
	v_fma_f32 v129, v137, v189, -v128
	v_floor_f32_e32 v138, v138
	v_sin_f32_e32 v128, v129
	v_cos_f32_e32 v129, v129
	v_fma_f32 v138, v142, v189, -v138
	v_mul_f32_e32 v142, v144, v189
	v_floor_f32_e32 v142, v142
	v_fma_f32 v142, v144, v189, -v142
	v_sin_f32_e32 v131, v130
	v_cos_f32_e32 v130, v130
	v_mul_f32_e32 v132, v139, v189
	v_floor_f32_e32 v132, v132
	v_fma_f32 v133, v139, v189, -v132
	v_sin_f32_e32 v132, v133
	v_cos_f32_e32 v133, v133
	v_mul_f32_e32 v134, v140, v189
	v_floor_f32_e32 v134, v134
	v_fma_f32 v134, v140, v189, -v134
	v_sin_f32_e32 v135, v134
	v_cos_f32_e32 v134, v134
	v_mul_f32_e32 v136, v141, v189
	v_floor_f32_e32 v136, v136
	v_fma_f32 v137, v141, v189, -v136
	v_sin_f32_e32 v136, v137
	v_cos_f32_e32 v137, v137
	v_sin_f32_e32 v139, v138
	v_cos_f32_e32 v138, v138
	v_mul_f32_e32 v140, v143, v189
	v_floor_f32_e32 v140, v140
	v_fma_f32 v141, v143, v189, -v140
	v_sin_f32_e32 v140, v141
	v_cos_f32_e32 v141, v141
	v_sin_f32_e32 v143, v142
	v_cos_f32_e32 v142, v142
	s_add_u32 s0, s42, s0
	s_addc_u32 s1, s43, 0
	v_lshlrev_b32_e32 v206, 3, v186
	s_add_u32 s0, s0, s8
	s_addc_u32 s1, s1, 0
	v_pk_mul_f32 v[38:39], v[38:39], v[38:39]
	v_lshlrev_b32_e32 v221, 8, v187
	v_pk_fma_f32 v[36:37], v[36:37], v[36:37], v[38:39]
	v_pk_mul_f32 v[38:39], v[40:41], v[40:41]
	v_and_b32_e32 v208, 63, v186
	v_pk_fma_f32 v[32:33], v[32:33], v[32:33], v[38:39]
	v_and_b32_e32 v39, 24, v206
	v_pk_add_f32 v[32:33], v[36:37], v[32:33]
	v_pk_mul_f32 v[36:37], v[44:45], v[44:45]
	s_cmp_lg_u32 0, -1
	v_pk_fma_f32 v[36:37], v[42:43], v[42:43], v[36:37]
	s_mul_i32 s9, s6, 0x8200000
	v_pk_add_f32 v[32:33], v[36:37], v[32:33]
	v_pk_mul_f32 v[36:37], v[46:47], v[46:47]
	s_cselect_b32 s6, 0, 0
	v_pk_fma_f32 v[34:35], v[34:35], v[34:35], v[36:37]
	v_lshrrev_b32_e32 v36, 5, v186
	v_pk_add_f32 v[32:33], v[34:35], v[32:33]
	v_pk_mul_f32 v[34:35], v[50:51], v[50:51]
	v_bfe_u32 v37, v206, 5, 2
	v_pk_fma_f32 v[34:35], v[48:49], v[48:49], v[34:35]
	v_and_or_b32 v36, v36, s58, v37
	v_pk_add_f32 v[32:33], v[34:35], v[32:33]
	v_pk_mul_f32 v[34:35], v[54:55], v[54:55]
	v_mov_b32_e32 v244, 1.0
	v_pk_fma_f32 v[34:35], v[52:53], v[52:53], v[34:35]
	s_mov_b32 s76, 0x10000
	v_pk_add_f32 v[32:33], v[34:35], v[32:33]
	v_pk_mul_f32 v[34:35], v[58:59], v[58:59]
	v_pk_mul_f32 v[58:59], v[120:121], v[120:121]
	v_pk_fma_f32 v[34:35], v[56:57], v[56:57], v[34:35]
	s_mov_b32 s77, 0x8000
	s_waitcnt vmcnt(3)
; __device__ __forceinline__ unsigned cvtpk(float lo, float hi) { unsigned r; asm volatile("v_cvt_pk_bf16_f32 %0, %1, %2" : "=v"(r) : "v"(lo), "v"(hi)); return r; }
; __device__ __forceinline__ float bflo(unsigned w) { return __uint_as_float(w << 16); }
; __device__ __forceinline__ float bfhi(unsigned w) { return __uint_as_float(w & 0xffff0000u); }
; __device__ __forceinline__ float sin_rev(float rev) { return __builtin_amdgcn_sinf(rev); }
; __device__ __forceinline__ void attn_item(const bf16_t* __restrict__ Qb, const bf16_t* __restrict__ Kh, const bf16_t* __restrict__ Vh, const bf16_t* __restrict__ Zb, ...
;     ...
;     for (int bb = 0; bb < 4; ++bb) { const int d1 = (bb & 1) + 4 * (bb >> 1), d2 = d1 + 2;
;       const float pos = (bb < 2) ? prow : pcol; const float* g1p = qg + d1 * 16 + hq * 8; const float* g2p = qg + d2 * 16 + hq * 8;
;       const f32x4 g1a = *(const f32x4*)g1p, g1b = *(const f32x4*)(g1p + 4), g2a = *(const f32x4*)g2p, g2b = *(const f32x4*)(g2p + 4);
;       float o1[8], o2[8];
; #pragma unroll
;       for (int e = 0; e < 8; ++e) { const unsigned w1 = (e < 2) ? qw[d1].x : (e < 4) ? qw[d1].y : (e < 6) ? qw[d1].z : qw[d1].w, w2 = (e < 2) ? qw[d2].x : (e < 4) ? qw[d2].y : (e < 6) ? qw[d2].z : qw[d2].w;
;         const float x1 = (e & 1) ? bfhi(w1) : bflo(w1), x2 = (e & 1) ? bfhi(w2) : bflo(w2); const float ga = (e < 4) ? g1a[e & 3] : g1b[e & 3], gb = (e < 4) ? g2a[e & 3] : g2b[e & 3];
;         const int fi = (d1 & 1) * 16 + hq * 8 + e; float rev = pos * (__builtin_amdgcn_exp2f(-(float)fi * (13.287712379549449f / 32.0f)) * 0.15915494309189535f); rev -= floorf(rev);
;         const float sn = sin_rev(rev), cs = cos_rev(rev), y1 = x1 * rstd * ga, y2 = x2 * rstd * gb; o1[e] = y1 * cs - y2 * sn; o2[e] = y2 * cs + y1 * sn; }
; #pragma unroll
;       for (int e = 0; e < 8; ++e) qn2 += o1[e] * o1[e] + o2[e] * o2[e];
;       u32x4 p1 = {cvtpk(o1[0], o1[1]), cvtpk(o1[2], o1[3]), cvtpk(o1[4], o1[5]), cvtpk(o1[6], o1[7])}, p2 = {cvtpk(o2[0], o2[1]), cvtpk(o2[2], o2[3]), cvtpk(o2[4], o2[5]), cvtpk(o2[6], o2[7])};
;       qr[d1] = *reinterpret_cast<bf16x8*>(&p1); qr[d2] = *reinterpret_cast<bf16x8*>(&p2); }
;   }
;   const int sr = tid >> 4, sc = (tid & 15) * 8, vst0 = v_st_nat(sr, sc), vst1 = v_st_nat(32 + sr, sc), kst0 = KOFF + KSWZ(sr, sc * 2), kst1 = KOFF + KSWZ(32 + sr, sc * 2);
	v_mov_b32_e32 v144, v2
	s_waitcnt vmcnt(2)
	v_mov_b32_e32 v145, v6
	v_pk_mul_f32 v[144:145], v[102:103], v[144:145]
	v_mov_b32_e32 v102, v129
	v_mov_b32_e32 v103, v128
	v_mul_f32_e32 v2, v128, v145
	v_pk_fma_f32 v[102:103], v[102:103], v[144:145], v[2:3] op_sel_hi:[1,1,0] neg_lo:[0,0,1] neg_hi:[0,0,1]
	v_mul_f32_e32 v2, v129, v145
	v_mov_b32_e32 v6, v3
	v_pk_fma_f32 v[128:129], v[128:129], v[144:145], v[2:3] op_sel_hi:[1,1,0]
	v_pk_mul_f32 v[2:3], v[94:95], v[6:7]
	v_mul_f32_e32 v144, v177, v189
	v_mul_f32_e32 v6, v131, v3
	v_pk_fma_f32 v[94:95], v[130:131], v[2:3], v[6:7] op_sel_hi:[1,1,0] neg_lo:[0,0,1] neg_hi:[0,0,1]
	v_mov_b32_e32 v6, v131
	v_mov_b32_e32 v7, v130
	v_mul_f32_e32 v130, v130, v3
	v_pk_fma_f32 v[130:131], v[6:7], v[2:3], v[130:131] op_sel_hi:[1,1,0]
	v_pk_mul_f32 v[2:3], v[0:1], v[92:93] op_sel_hi:[0,1]
	v_mov_b32_e32 v6, v4
	v_mov_b32_e32 v7, v8
	v_pk_mul_f32 v[2:3], v[2:3], v[6:7]
	v_mov_b32_e32 v6, v133
	v_mov_b32_e32 v7, v132
	v_mul_f32_e32 v4, v132, v3
	v_pk_fma_f32 v[92:93], v[6:7], v[2:3], v[4:5] op_sel_hi:[1,1,0] neg_lo:[0,0,1] neg_hi:[0,0,1]
	v_mul_f32_e32 v4, v133, v3
	v_pk_fma_f32 v[132:133], v[132:133], v[2:3], v[4:5] op_sel_hi:[1,1,0]
	v_pk_mul_f32 v[2:3], v[0:1], v[90:91] op_sel_hi:[0,1]
	v_mov_b32_e32 v8, v5
	v_pk_mul_f32 v[2:3], v[2:3], v[8:9]
	v_cvt_pk_bf16_f32 v168, v102, v94
	v_floor_f32_e32 v144, v144
	v_mul_f32_e32 v4, v135, v3
	v_pk_fma_f32 v[90:91], v[134:135], v[2:3], v[4:5] op_sel_hi:[1,1,0] neg_lo:[0,0,1] neg_hi:[0,0,1]
	v_mov_b32_e32 v4, v135
	v_mov_b32_e32 v5, v134
	v_mul_f32_e32 v6, v134, v3
	v_pk_fma_f32 v[134:135], v[4:5], v[2:3], v[6:7] op_sel_hi:[1,1,0]
	v_pk_mul_f32 v[2:3], v[0:1], v[88:89] op_sel_hi:[0,1]
	s_waitcnt vmcnt(1)
	v_mov_b32_e32 v4, v10
	s_waitcnt vmcnt(0)
	v_mov_b32_e32 v5, v164
	v_pk_mul_f32 v[2:3], v[2:3], v[4:5]
	v_mov_b32_e32 v4, v137
	v_mov_b32_e32 v5, v136
	v_mul_f32_e32 v6, v136, v3
	v_pk_fma_f32 v[88:89], v[4:5], v[2:3], v[6:7] op_sel_hi:[1,1,0] neg_lo:[0,0,1] neg_hi:[0,0,1]
	v_mul_f32_e32 v4, v137, v3
	v_pk_fma_f32 v[136:137], v[136:137], v[2:3], v[4:5] op_sel_hi:[1,1,0]
	v_pk_mul_f32 v[2:3], v[0:1], v[86:87] op_sel_hi:[0,1]
	v_mov_b32_e32 v164, v11
	v_pk_mul_f32 v[2:3], v[2:3], v[164:165]
	v_cvt_pk_bf16_f32 v169, v92, v90
	v_fma_f32 v144, v177, v189, -v144
	v_mul_f32_e32 v4, v139, v3
	v_pk_fma_f32 v[86:87], v[138:139], v[2:3], v[4:5] op_sel_hi:[1,1,0] neg_lo:[0,0,1] neg_hi:[0,0,1]
	v_mov_b32_e32 v4, v139
	v_mov_b32_e32 v5, v138
	v_mul_f32_e32 v6, v138, v3
	v_pk_fma_f32 v[138:139], v[4:5], v[2:3], v[6:7] op_sel_hi:[1,1,0]
	v_pk_mul_f32 v[2:3], v[0:1], v[84:85] op_sel_hi:[0,1]
	v_mov_b32_e32 v4, v12
	v_mov_b32_e32 v5, v166
	v_pk_mul_f32 v[2:3], v[2:3], v[4:5]
	v_mov_b32_e32 v4, v141
	v_mov_b32_e32 v5, v140
	v_mul_f32_e32 v6, v140, v3
	v_pk_fma_f32 v[84:85], v[4:5], v[2:3], v[6:7] op_sel_hi:[1,1,0] neg_lo:[0,0,1] neg_hi:[0,0,1]
	v_mul_f32_e32 v4, v141, v3
	v_pk_fma_f32 v[140:141], v[140:141], v[2:3], v[4:5] op_sel_hi:[1,1,0]
	v_pk_mul_f32 v[2:3], v[0:1], v[80:81] op_sel_hi:[0,1]
	v_mov_b32_e32 v166, v13
	v_pk_mul_f32 v[2:3], v[2:3], v[166:167]
	v_cvt_pk_bf16_f32 v170, v88, v86
	v_sin_f32_e32 v147, v144
	v_mul_f32_e32 v4, v143, v3
	v_pk_fma_f32 v[80:81], v[142:143], v[2:3], v[4:5] op_sel_hi:[1,1,0] neg_lo:[0,0,1] neg_hi:[0,0,1]
	v_mov_b32_e32 v4, v143
	v_mov_b32_e32 v5, v142
	v_mul_f32_e32 v6, v142, v3
	v_pk_fma_f32 v[142:143], v[4:5], v[2:3], v[6:7] op_sel_hi:[1,1,0]
	v_cvt_pk_bf16_f32 v171, v84, v80
	v_cvt_pk_bf16_f32 v164, v128, v130
	v_cvt_pk_bf16_f32 v165, v132, v134
	v_cvt_pk_bf16_f32 v166, v136, v138
	v_cos_f32_e32 v146, v144
	v_cvt_pk_bf16_f32 v167, v140, v142
	global_load_dwordx4 v[2:5], v[14:15], off offset:320
	global_load_dwordx4 v[6:9], v[14:15], off offset:448
	global_load_dwordx4 v[10:13], v[14:15], off offset:336
	global_load_dwordx4 v[172:175], v[14:15], off offset:464
	v_mul_f32_e32 v144, v178, v189
	v_mul_f32_e32 v14, v176, v189
	v_floor_f32_e32 v144, v144
	v_floor_f32_e32 v14, v14
	v_fma_f32 v144, v178, v189, -v144
	v_fma_f32 v15, v176, v189, -v14
	v_sin_f32_e32 v176, v144
	v_cos_f32_e32 v177, v144
	v_mul_f32_e32 v144, v179, v189
	v_floor_f32_e32 v144, v144
	v_fma_f32 v144, v179, v189, -v144
	v_sin_f32_e32 v179, v144
	v_cos_f32_e32 v178, v144
	v_mul_f32_e32 v144, v180, v189
	v_floor_f32_e32 v144, v144
	v_fma_f32 v144, v180, v189, -v144
	v_sin_f32_e32 v184, v144
	v_cos_f32_e32 v185, v144
	v_mul_f32_e32 v144, v181, v189
	v_floor_f32_e32 v144, v144
	v_fma_f32 v144, v181, v189, -v144
	v_sin_f32_e32 v191, v144
	v_cos_f32_e32 v190, v144
	v_mul_f32_e32 v144, v182, v189
	v_floor_f32_e32 v144, v144
	v_fma_f32 v144, v182, v189, -v144
	v_sin_f32_e32 v192, v144
	v_cos_f32_e32 v193, v144
	v_mul_f32_e32 v144, v183, v189
	v_sin_f32_e32 v14, v15
	v_cos_f32_e32 v15, v15
	v_floor_f32_e32 v144, v144
	v_fma_f32 v144, v183, v189, -v144
	v_sin_f32_e32 v195, v144
	v_cos_f32_e32 v194, v144
	v_ashrrev_i32_e32 v189, 4, v186
	v_add_u32_e32 v207, 32, v189
	v_pk_add_f32 v[32:33], v[34:35], v[32:33]
	v_pk_mul_f32 v[34:35], v[82:83], v[82:83]
	v_lshlrev_b32_e32 v38, 5, v189
	v_pk_fma_f32 v[34:35], v[64:65], v[64:65], v[34:35]
	v_and_or_b32 v38, v38, s59, v39
	v_pk_add_f32 v[32:33], v[34:35], v[32:33]
	v_pk_mul_f32 v[34:35], v[96:97], v[96:97]
	v_lshlrev_b32_e32 v38, 1, v38
	v_pk_fma_f32 v[34:35], v[78:79], v[78:79], v[34:35]
	v_lshl_or_b32 v228, v36, 9, v38
	v_pk_add_f32 v[32:33], v[34:35], v[32:33]
	v_pk_mul_f32 v[34:35], v[108:109], v[108:109]
	v_lshrrev_b32_e32 v36, 1, v207
	v_pk_fma_f32 v[34:35], v[104:105], v[104:105], v[34:35]
	v_and_or_b32 v36, v36, s58, v37
	v_lshlrev_b32_e32 v82, 4, v186
	v_add_u32_e32 v108, 0, v228
	v_pk_add_f32 v[32:33], v[34:35], v[32:33]
	v_pk_mul_f32 v[34:35], v[116:117], v[116:117]
	v_lshl_or_b32 v229, v36, 9, v38
	v_lshlrev_b32_e32 v36, 8, v189
	v_and_b32_e32 v38, 0xf0, v186
	v_lshlrev_b32_e32 v39, 8, v207
	v_pk_fma_f32 v[34:35], v[112:113], v[112:113], v[34:35]
	v_add_u32_e32 v83, 0, v221
	v_pk_add_f32 v[32:33], v[34:35], v[32:33]
	v_pk_mul_f32 v[34:35], v[124:125], v[124:125]
	v_add_u32_e32 v109, 0, v229
	v_pk_fma_f32 v[34:35], v[122:123], v[122:123], v[34:35]
	v_pk_mul_f32 v[78:79], v[126:127], v[126:127]
	v_pk_add_f32 v[32:33], v[34:35], v[32:33]
	v_pk_mul_f32 v[34:35], v[100:101], v[100:101]
	s_mov_b32 s78, -1
	v_pk_fma_f32 v[34:35], v[98:99], v[98:99], v[34:35]
	v_mov_b32_e32 v219, 0
	v_pk_add_f32 v[32:33], v[34:35], v[32:33]
	v_pk_mul_f32 v[34:35], v[110:111], v[110:111]
	s_waitcnt vmcnt(3)
; __device__ __forceinline__ unsigned cvtpk(float lo, float hi) { unsigned r; asm volatile("v_cvt_pk_bf16_f32 %0, %1, %2" : "=v"(r) : "v"(lo), "v"(hi)); return r; }
; __device__ __forceinline__ float bflo(unsigned w) { return __uint_as_float(w << 16); }
; __device__ __forceinline__ float bfhi(unsigned w) { return __uint_as_float(w & 0xffff0000u); }
; __device__ __forceinline__ float sin_rev(float rev) { return __builtin_amdgcn_sinf(rev); }
; __device__ __forceinline__ float cos_rev(float rev) { return __builtin_amdgcn_cosf(rev); }
; #define SWAIT() asm volatile("s_waitcnt vmcnt(0)" ::: "memory")
; __device__ __forceinline__ void attn_item(const bf16_t* __restrict__ Qb, const bf16_t* __restrict__ Kh, const bf16_t* __restrict__ Vh, const bf16_t* __restrict__ Zb, ...
;     ...
;       for (int e = 0; e < 8; ++e) { const unsigned w1 = (e < 2) ? qw[d1].x : (e < 4) ? qw[d1].y : (e < 6) ? qw[d1].z : qw[d1].w, w2 = (e < 2) ? qw[d2].x : (e < 4) ? qw[d2].y : (e < 6) ? qw[d2].z : qw[d2].w;
;         const float x1 = (e & 1) ? bfhi(w1) : bflo(w1), x2 = (e & 1) ? bfhi(w2) : bflo(w2); const float ga = (e < 4) ? g1a[e & 3] : g1b[e & 3], gb = (e < 4) ? g2a[e & 3] : g2b[e & 3];
;         const int fi = (d1 & 1) * 16 + hq * 8 + e; float rev = pos * (__builtin_amdgcn_exp2f(-(float)fi * (13.287712379549449f / 32.0f)) * 0.15915494309189535f); rev -= floorf(rev);
;         const float sn = sin_rev(rev), cs = cos_rev(rev), y1 = x1 * rstd * ga, y2 = x2 * rstd * gb; o1[e] = y1 * cs - y2 * sn; o2[e] = y2 * cs + y1 * sn; }
; #pragma unroll
;       for (int e = 0; e < 8; ++e) qn2 += o1[e] * o1[e] + o2[e] * o2[e];
;       u32x4 p1 = {cvtpk(o1[0], o1[1]), cvtpk(o1[2], o1[3]), cvtpk(o1[4], o1[5]), cvtpk(o1[6], o1[7])}, p2 = {cvtpk(o2[0], o2[1]), cvtpk(o2[2], o2[3]), cvtpk(o2[4], o2[5]), cvtpk(o2[6], o2[7])};
;       qr[d1] = *reinterpret_cast<bf16x8*>(&p1); qr[d2] = *reinterpret_cast<bf16x8*>(&p2); }
;   }
;   const int sr = tid >> 4, sc = (tid & 15) * 8, vst0 = v_st_nat(sr, sc), vst1 = v_st_nat(32 + sr, sc), kst0 = KOFF + KSWZ(sr, sc * 2), kst1 = KOFF + KSWZ(32 + sr, sc * 2);
;   const int vb0 = (int)(uintptr_t)lds + v_rd_base(lane);
;   struct { bf16x8 vs0, vs1, ks0, ks1; } sr_;
;     ...
;   f32x16 pA0, pA1, pB0, pB1; float alA, alB; VF8 vfa; bf16x8 pa0, pa1, pa2, pa3; const int NT = seq / KVBLK;
;   int s_prev = 0, s_cur = SLOT, s_next = 2 * SLOT;
;   SLOAD(0); SWAIT(); SWRITE(0); __syncthreads();
	v_mov_b32_e32 v144, v2
	s_waitcnt vmcnt(2)
	v_mov_b32_e32 v145, v6
	v_pk_mul_f32 v[144:145], v[76:77], v[144:145]
	v_mov_b32_e32 v76, v15
	v_mov_b32_e32 v77, v14
	v_mul_f32_e32 v2, v14, v145
	v_pk_fma_f32 v[76:77], v[76:77], v[144:145], v[2:3] op_sel_hi:[1,1,0] neg_lo:[0,0,1] neg_hi:[0,0,1]
	v_mul_f32_e32 v2, v15, v145
	v_pk_fma_f32 v[144:145], v[14:15], v[144:145], v[2:3] op_sel_hi:[1,1,0]
	v_pk_mul_f32 v[14:15], v[0:1], v[60:61] op_sel_hi:[0,1]
	v_mov_b32_e32 v6, v3
	v_pk_mul_f32 v[2:3], v[14:15], v[6:7]
	v_pk_fma_f32 v[34:35], v[106:107], v[106:107], v[34:35]
	v_mul_f32_e32 v6, v147, v3
	v_pk_fma_f32 v[60:61], v[146:147], v[2:3], v[6:7] op_sel_hi:[1,1,0] neg_lo:[0,0,1] neg_hi:[0,0,1]
	v_mov_b32_e32 v6, v147
	v_mov_b32_e32 v7, v146
	v_mul_f32_e32 v14, v146, v3
	v_pk_fma_f32 v[146:147], v[6:7], v[2:3], v[14:15] op_sel_hi:[1,1,0]
	v_pk_mul_f32 v[2:3], v[0:1], v[74:75] op_sel_hi:[0,1]
	v_mov_b32_e32 v6, v4
	v_mov_b32_e32 v7, v8
	v_pk_mul_f32 v[2:3], v[2:3], v[6:7]
	v_mov_b32_e32 v6, v177
	v_mov_b32_e32 v7, v176
	v_mul_f32_e32 v4, v176, v3
	v_pk_fma_f32 v[74:75], v[6:7], v[2:3], v[4:5] op_sel_hi:[1,1,0] neg_lo:[0,0,1] neg_hi:[0,0,1]
	v_mul_f32_e32 v4, v177, v3
	v_pk_fma_f32 v[180:181], v[176:177], v[2:3], v[4:5] op_sel_hi:[1,1,0]
	v_pk_mul_f32 v[2:3], v[0:1], v[66:67] op_sel_hi:[0,1]
	v_mov_b32_e32 v8, v5
	v_pk_mul_f32 v[2:3], v[2:3], v[8:9]
	s_waitcnt vmcnt(0)
	v_mov_b32_e32 v15, v174
	v_mul_f32_e32 v4, v179, v3
	v_pk_fma_f32 v[66:67], v[178:179], v[2:3], v[4:5] op_sel_hi:[1,1,0] neg_lo:[0,0,1] neg_hi:[0,0,1]
	v_mov_b32_e32 v4, v179
	v_mov_b32_e32 v5, v178
	v_mul_f32_e32 v6, v178, v3
	v_pk_fma_f32 v[182:183], v[4:5], v[2:3], v[6:7] op_sel_hi:[1,1,0]
	v_pk_mul_f32 v[2:3], v[0:1], v[72:73] op_sel_hi:[0,1]
	v_mov_b32_e32 v4, v10
	v_mov_b32_e32 v5, v172
	v_pk_mul_f32 v[6:7], v[0:1], v[62:63] op_sel_hi:[0,1]
	v_mov_b32_e32 v172, v11
	v_pk_mul_f32 v[2:3], v[2:3], v[4:5]
	v_mov_b32_e32 v4, v185
	v_mov_b32_e32 v5, v184
	v_pk_mul_f32 v[6:7], v[6:7], v[172:173]
	v_mov_b32_e32 v10, v191
	v_mov_b32_e32 v11, v190
	v_pk_mul_f32 v[62:63], v[0:1], v[70:71] op_sel_hi:[0,1]
	v_mov_b32_e32 v174, v13
	v_pk_mul_f32 v[4:5], v[4:5], v[2:3]
	v_pk_mul_f32 v[8:9], v[190:191], v[6:7]
	v_pk_mul_f32 v[6:7], v[10:11], v[6:7]
	v_pk_mul_f32 v[10:11], v[0:1], v[68:69] op_sel_hi:[0,1]
	v_mov_b32_e32 v14, v12
	v_pk_mul_f32 v[12:13], v[62:63], v[174:175]
	v_mov_b32_e32 v62, v195
	v_mov_b32_e32 v63, v194
	v_pk_mul_f32 v[2:3], v[184:185], v[2:3]
	v_pk_mul_f32 v[10:11], v[10:11], v[14:15]
	v_mov_b32_e32 v14, v193
	v_mov_b32_e32 v15, v192
	v_pk_mul_f32 v[68:69], v[194:195], v[12:13]
	v_pk_mul_f32 v[12:13], v[62:63], v[12:13]
	v_mov_b32_e32 v62, v8
	v_mov_b32_e32 v63, v4
	v_mov_b32_e32 v4, v9
	v_pk_mul_f32 v[14:15], v[14:15], v[10:11]
	v_pk_add_f32 v[62:63], v[62:63], v[4:5] neg_lo:[0,1] neg_hi:[0,1]
	v_mov_b32_e32 v4, v6
	v_mov_b32_e32 v5, v2
	v_mov_b32_e32 v2, v7
	v_pk_mul_f32 v[10:11], v[192:193], v[10:11]
	v_pk_add_f32 v[72:73], v[4:5], v[2:3]
	v_mov_b32_e32 v2, v68
	v_mov_b32_e32 v3, v14
	v_mov_b32_e32 v14, v69
	v_pk_add_f32 v[68:69], v[2:3], v[14:15] neg_lo:[0,1] neg_hi:[0,1]
	v_mov_b32_e32 v2, v12
	v_mov_b32_e32 v3, v10
	v_mov_b32_e32 v10, v13
	v_and_b32_e32 v70, 0x78, v206
	v_mov_b32_e32 v71, v1
	v_pk_add_f32 v[184:185], v[2:3], v[10:11]
	v_mad_i64_i32 v[2:3], s[36:37], v189, s61, v[70:71]
	v_lshl_add_u64 v[2:3], v[2:3], 1, s[0:1]
	v_cvt_pk_bf16_f32 v176, v76, v60
	v_cvt_pk_bf16_f32 v177, v74, v66
	v_cvt_pk_bf16_f32 v178, v63, v62
	v_cvt_pk_bf16_f32 v179, v69, v68
	v_cvt_pk_bf16_f32 v172, v144, v146
	v_cvt_pk_bf16_f32 v173, v180, v182
	v_cvt_pk_bf16_f32 v174, v73, v72
	v_cvt_pk_bf16_f32 v175, v185, v184
	global_load_dwordx4 v[190:193], v[2:3], off offset:2560
	v_mad_i64_i32 v[4:5], s[36:37], v207, s61, v[70:71]
	v_lshl_add_u64 v[4:5], v[4:5], 1, s[0:1]
	global_load_dwordx4 v[194:197], v[4:5], off offset:2560
	global_load_dwordx4 v[198:201], v[2:3], off offset:2048
	global_load_dwordx4 v[202:205], v[4:5], off offset:2048
	v_lshlrev_b32_e32 v37, 1, v70
	s_waitcnt vmcnt(0)
	v_bitop3_b32 v231, v37, v36, v38 bitop3:0xde
	v_bitop3_b32 v232, v39, v37, v38 bitop3:0xf6
	v_add_u32_e32 v112, 0, v231
	v_add_u32_e32 v113, 0, v232
	v_pk_add_f32 v[56:57], v[34:35], v[32:33]
	v_and_b32_e32 v0, 0x3fffffc0, v186
	v_mov_b32_e32 v14, v1
	v_mov_b32_e32 v15, v1
	v_lshl_add_u32 v213, v0, 2, s56
	v_mov_b32_e32 v0, v1
	v_mov_b32_e32 v2, v1
	v_mov_b32_e32 v3, v1
	v_mov_b32_e32 v4, v1
	v_mov_b32_e32 v5, v1
	v_mov_b32_e32 v6, v1
	v_mov_b32_e32 v7, v1
	v_mov_b32_e32 v8, v1
	v_mov_b32_e32 v9, v1
	v_mov_b32_e32 v10, v1
	v_mov_b32_e32 v11, v1
	v_mov_b32_e32 v12, v1
	v_mov_b32_e32 v13, v1
	v_or_b32_e32 v106, 0xc0, v212
	v_or_b32_e32 v107, 0xe0, v212
	v_lshl_add_u32 v220, v187, 2, v213
	s_waitcnt vmcnt(3)
	ds_write_b128 v108, v[190:193]
	v_and_b32_e32 v190, 0xf0, v82
	v_bitop3_b32 v234, v188, v190, 16 bitop3:0x6c
	v_add_u32_e32 v36, v83, v234
	s_waitcnt vmcnt(2)
	ds_write_b128 v109, v[194:197]
	s_waitcnt vmcnt(1)
	ds_write_b128 v112, v[198:201] offset:16384
	s_waitcnt vmcnt(0)
	ds_write_b128 v113, v[202:205] offset:16384
	s_waitcnt lgkmcnt(0)
	s_barrier
; #define SLOAD(k0) do { sr_.vs0 = *(const bf16x8*)(&Vh[(long)((k0) + sr) * LDK + sc]); sr_.vs1 = *(const bf16x8*)(&Vh[(long)((k0) + 32 + sr) * LDK + sc]); \
;     sr_.ks0 = *(const bf16x8*)(&Kh[(long)((k0) + sr) * LDK + sc]); sr_.ks1 = *(const bf16x8*)(&Kh[(long)((k0) + 32 + sr) * LDK + sc]); } while (0)
; __device__ __forceinline__ void qkt(f32x16& p0, f32x16& p1, const bf16_t* Ks, const bf16x8* qr, const f32x16& negm, int r32, int hi) {
; #pragma unroll
;   for (int d0 = 0; d0 < 8; ++d0) { int cb = (d0 * 16 + hi * 8) * 2;
;     bf16x8 b0 = *reinterpret_cast<const bf16x8*>((const char*)Ks + KSWZ(r32, cb));
;     bf16x8 b1 = *reinterpret_cast<const bf16x8*>((const char*)Ks + KSWZ(32 + r32, cb));
;     if (d0 == 0) { p0 = __builtin_amdgcn_mfma_f32_32x32x16_bf16(b0, qr[0], negm, 0, 0, 0); p1 = __builtin_amdgcn_mfma_f32_32x32x16_bf16(b1, qr[0], negm, 0, 0, 0); }
;     else { p0 = __builtin_amdgcn_mfma_f32_32x32x16_bf16(b0, qr[d0], p0, 0, 0, 0); p1 = __builtin_amdgcn_mfma_f32_32x32x16_bf16(b1, qr[d0], p1, 0, 0, 0); } }
; __device__ __forceinline__ void attn_item(const bf16_t* __restrict__ Qb, const bf16_t* __restrict__ Kh, const bf16_t* __restrict__ Vh, const bf16_t* __restrict__ Zb, ...
;     ...
;   SLOAD(KVBLK);
;   qkt(pA0, pA1, (const bf16_t*)(lds + KOFF), qr, negm, r32, hi); partialSM<true>(pA0, pA1, m_reg, negm, alA);
	ds_read_b128 v[48:51], v36 offset:24576
	ds_read_b128 v[52:55], v36 offset:16384
	s_waitcnt lgkmcnt(0)
	v_mfma_f32_32x32x16_bf16 v[32:47], v[52:55], v[152:155], v[16:31]
	v_fma_f32 v52, v114, v114, v58
	v_fma_f32 v53, v115, v115, v59
	v_bitop3_b32 v233, v212, v190, 32 bitop3:0x36
	v_add_f32_e64 v64, v52, v56
	v_add_f32_e64 v65, v53, v57
	v_add_u32_e32 v56, v83, v233
	ds_read_b128 v[52:55], v56 offset:24576
	ds_read_b128 v[56:59], v56 offset:16384
	v_bitop3_b32 v230, v212, v190, 64 bitop3:0x36
	v_bitop3_b32 v227, v212, v190, s62 bitop3:0x36
	v_mfma_f32_32x32x16_bf16 v[16:31], v[48:51], v[152:155], v[16:31]
	v_fma_f32 v48, v118, v118, v78
	v_fma_f32 v49, v119, v119, v79
	v_mul_f32_e64 v50, v128, v128
	v_mul_f32_e64 v51, v129, v129
	v_add_f32_e64 v48, v48, v64
	v_add_f32_e64 v49, v49, v65
	v_pk_fma_f32 v[50:51], v[102:103], v[102:103], v[50:51]
	v_bitop3_b32 v226, v212, v190, s63 bitop3:0x36
	v_pk_add_f32 v[48:49], v[48:49], v[50:51]
	v_pk_mul_f32 v[50:51], v[130:131], v[130:131]
	s_waitcnt lgkmcnt(0)
	v_mfma_f32_32x32x16_bf16 v[32:47], v[56:59], v[160:163], v[32:47]
	v_fma_f32 v50, v94, v94, v50
	v_fma_f32 v51, v95, v95, v51
	v_add_u32_e32 v56, v83, v230
	v_add_f32_e64 v64, v50, v48
	v_add_f32_e64 v65, v51, v49
	v_pk_mul_f32 v[48:49], v[132:133], v[132:133]
	v_bitop3_b32 v225, v212, v190, s64 bitop3:0x36
	v_pk_fma_f32 v[78:79], v[92:93], v[92:93], v[48:49]
	ds_read_b128 v[48:51], v56 offset:24576
	ds_read_b128 v[56:59], v56 offset:16384
	v_mfma_f32_32x32x16_bf16 v[16:31], v[52:55], v[160:163], v[16:31]
	v_mul_f32_e64 v54, v134, v134
	v_mul_f32_e64 v55, v135, v135
	v_add_f32_e64 v52, v78, v64
	v_add_f32_e64 v53, v79, v65
	v_fma_f32 v54, v90, v90, v54
	v_fma_f32 v55, v91, v91, v55
	v_bitop3_b32 v224, v212, v190, s60 bitop3:0x36
	v_pk_add_f32 v[52:53], v[54:55], v[52:53]
	v_pk_mul_f32 v[54:55], v[136:137], v[136:137]
	v_bitop3_b32 v223, v212, v190, s59 bitop3:0x36
	v_pk_fma_f32 v[54:55], v[88:89], v[88:89], v[54:55]
	s_waitcnt lgkmcnt(0)
	v_mfma_f32_32x32x16_bf16 v[32:47], v[56:59], v[148:151], v[32:47]
	v_add_f32_e64 v52, v54, v52
	v_add_f32_e64 v53, v55, v53
	v_mul_f32_e64 v54, v138, v138
	v_mul_f32_e64 v55, v139, v139
	v_add_u32_e32 v56, v83, v227
	v_pk_fma_f32 v[54:55], v[86:87], v[86:87], v[54:55]
	v_bitop3_b32 v236, v212, v221, v190 bitop3:0xde
	v_pk_add_f32 v[64:65], v[54:55], v[52:53]
	ds_read_b128 v[52:55], v56 offset:24576
	ds_read_b128 v[56:59], v56 offset:16384
	v_mfma_f32_32x32x16_bf16 v[16:31], v[48:51], v[148:151], v[16:31]
	v_mul_f32_e64 v48, v140, v140
	v_mul_f32_e64 v49, v141, v141
	v_mul_f32_e64 v50, v142, v142
	v_mul_f32_e64 v51, v143, v143
	v_fma_f32 v48, v84, v84, v48
	v_fma_f32 v49, v85, v85, v49
	v_pk_fma_f32 v[50:51], v[80:81], v[80:81], v[50:51]
	v_pk_add_f32 v[48:49], v[48:49], v[64:65]
	v_bitop3_b32 v242, v106, v221, v190 bitop3:0xde
	v_pk_add_f32 v[48:49], v[50:51], v[48:49]
	s_waitcnt lgkmcnt(0)
	v_mfma_f32_32x32x16_bf16 v[32:47], v[56:59], v[156:159], v[32:47]
	v_mul_f32_e64 v50, v144, v144
	v_mul_f32_e64 v51, v145, v145
	v_add_u32_e32 v56, v83, v226
	v_fma_f32 v50, v76, v76, v50
	v_fma_f32 v51, v77, v77, v51
	v_pk_mul_f32 v[76:77], v[146:147], v[146:147]
	v_pk_add_f32 v[64:65], v[48:49], v[50:51]
	ds_read_b128 v[48:51], v56 offset:24576
	ds_read_b128 v[56:59], v56 offset:16384
	v_bitop3_b32 v243, v107, v221, v190 bitop3:0xde
	v_mfma_f32_32x32x16_bf16 v[16:31], v[52:55], v[156:159], v[16:31]
	v_fma_f32 v52, v60, v60, v76
	v_fma_f32 v53, v61, v61, v77
	v_mul_f32_e64 v54, v180, v180
	v_mul_f32_e64 v55, v181, v181
	v_add_f32_e64 v52, v52, v64
	v_add_f32_e64 v53, v53, v65
	v_pk_fma_f32 v[54:55], v[74:75], v[74:75], v[54:55]
	s_nop 0
	v_pk_add_f32 v[52:53], v[54:55], v[52:53]
	v_pk_mul_f32 v[54:55], v[182:183], v[182:183]
	s_waitcnt lgkmcnt(0)
	v_mfma_f32_32x32x16_bf16 v[32:47], v[56:59], v[168:171], v[32:47]
	v_fma_f32 v54, v66, v66, v54
	v_fma_f32 v55, v67, v67, v55
	v_add_u32_e32 v56, v83, v225
	v_add_f32_e64 v60, v54, v52
	v_add_f32_e64 v61, v55, v53
	v_pk_mul_f32 v[52:53], v[72:73], v[72:73]
	s_nop 0
	v_pk_fma_f32 v[62:63], v[62:63], v[62:63], v[52:53]
	ds_read_b128 v[52:55], v56 offset:24576
	ds_read_b128 v[56:59], v56 offset:16384
	v_mfma_f32_32x32x16_bf16 v[16:31], v[48:51], v[168:171], v[16:31]
	v_add_f32_e64 v48, v63, v60
	v_add_f32_e64 v49, v62, v61
	v_mul_f32_e64 v50, v184, v184
	v_mul_f32_e64 v51, v185, v185
	v_add_f32_e64 v48, v62, v48
	v_add_f32_e64 v49, v63, v49
	v_pk_fma_f32 v[50:51], v[68:69], v[68:69], v[50:51]
	v_lshlrev_b32_e32 v60, 3, v208
	v_pk_add_f32 v[48:49], v[50:51], v[48:49] op_sel:[1,0] op_sel_hi:[0,1]
	v_pk_add_f32 v[64:65], v[50:51], v[48:49]
	s_waitcnt lgkmcnt(0)
	v_mfma_f32_32x32x16_bf16 v[32:47], v[56:59], v[176:179], v[32:47]
	v_and_b32_e32 v48, 0xc0, v82
	v_add_u32_e32 v56, v83, v224
	v_and_or_b32 v61, v60, 24, v48
	v_lshlrev_b32_e32 v62, 1, v186
	ds_read_b128 v[48:51], v56 offset:24576
	ds_read_b128 v[56:59], v56 offset:16384
	v_or_b32_e32 v65, 0xa0, v212
	v_bitop3_b32 v241, v65, v221, v190 bitop3:0xde
	v_mfma_f32_32x32x16_bf16 v[16:31], v[52:55], v[176:179], v[16:31]
	v_and_b32_e32 v52, 32, v62
	v_and_b32_e32 v53, 0x100, v60
	v_or3_b32 v52, v61, v52, v53
	v_add_u32_e32 v235, s6, v52
	v_add_u32_e32 v52, 64, v189
	v_mad_i64_i32 v[52:53], s[6:7], v52, s61, v[70:71]
	v_add_u32_e32 v62, 0x60, v189
	s_waitcnt lgkmcnt(0)
	v_mfma_f32_32x32x16_bf16 v[32:47], v[56:59], v[164:167], v[32:47]
	v_lshl_add_u64 v[60:61], v[52:53], 1, s[0:1]
	v_add_u32_e32 v56, v83, v223
	ds_read_b128 v[52:55], v56 offset:24576
	ds_read_b128 v[56:59], v56 offset:16384
	v_mfma_f32_32x32x16_bf16 v[16:31], v[48:51], v[164:167], v[16:31]
	v_mad_i64_i32 v[48:49], s[6:7], v62, s61, v[70:71]
	v_lshl_add_u64 v[66:67], v[48:49], 1, s[0:1]
	global_load_dwordx4 v[48:51], v[60:61], off offset:2560
	s_nop 0
	global_load_dwordx4 v[60:63], v[60:61], off offset:2048
	s_nop 0
	global_load_dwordx4 v[98:101], v[66:67], off offset:2560
	global_load_dwordx4 v[102:105], v[66:67], off offset:2048
	v_cmp_gt_u32_e64 s[6:7], 32, v208
	s_waitcnt lgkmcnt(0)
; template <bool FIRST, bool DOEXP = true>
; __device__ __forceinline__ void partialSM(f32x16& p0, f32x16& p1, float& m_reg, f32x16& negm, float& alpha, const bool track = true) {
;     ...
;   float pmax = p0[0];
; #pragma unroll
;   for (int r = 1; r < 16; ++r) pmax = fmaxf(pmax, p0[r]);
; #pragma unroll
;   for (int r = 0; r < 16; ++r) pmax = fmaxf(pmax, p1[r]);
;   { auto rr = __builtin_amdgcn_permlane32_swap(__float_as_uint(pmax), __float_as_uint(pmax), false, false);
;     pmax = fmaxf(__uint_as_float(rr[0]), __uint_as_float(rr[1])); }
;   if (!FIRST && __builtin_expect(__all(pmax <= THRL), 1)) { alpha = 1.f; }
;   else { const float dl = FIRST ? pmax : fmaxf(pmax, 0.f); m_reg += dl; alpha = FIRST ? 1.f : __builtin_amdgcn_exp2f(-dl);
; #pragma unroll
;     for (int r = 0; r < 16; ++r) { p0[r] -= dl; p1[r] -= dl; }
; #pragma unroll
;     for (int r = 0; r < 16; ++r) negm[r] = -m_reg;
;     asm volatile("" : "+v"(negm)); }
;   if (DOEXP) {
; #pragma unroll
;     for (int r = 0; r < 16; ++r) p0[r] = __builtin_amdgcn_exp2f(p0[r]); }
; __device__ __forceinline__ void attn_item(const bf16_t* __restrict__ Qb, const bf16_t* __restrict__ Kh, const bf16_t* __restrict__ Vh, const bf16_t* __restrict__ Zb, ...
;     ...
;   { auto rr = __builtin_amdgcn_permlane32_swap(__float_as_uint(qn2), __float_as_uint(qn2), false, false); qn2 = __uint_as_float(rr[0]) + __uint_as_float(rr[1]); }
;   const bool track = !__all(__builtin_sqrtf(qn2) * kmaxg - m_reg <= 90.f);
	v_mfma_f32_32x32x16_bf16 v[32:47], v[56:59], v[172:175], v[32:47]
	v_or_b32_e32 v56, 32, v212
	v_or_b32_e32 v57, 64, v212
	v_or_b32_e32 v58, 0x60, v212
	v_or_b32_e32 v59, 0x80, v212
	v_bitop3_b32 v237, v56, v221, v190 bitop3:0xde
	v_bitop3_b32 v238, v57, v221, v190 bitop3:0xde
	v_bitop3_b32 v239, v58, v221, v190 bitop3:0xde
	v_mfma_f32_32x32x16_bf16 v[16:31], v[52:55], v[172:175], v[16:31]
	s_nop 3
	v_max_f32_e32 v52, v32, v33
	v_max3_f32 v52, v52, v34, v35
	v_max3_f32 v52, v52, v36, v37
	v_max3_f32 v52, v52, v38, v39
	v_max3_f32 v52, v52, v40, v41
	v_max3_f32 v52, v52, v42, v43
	v_max3_f32 v52, v52, v44, v45
	v_max3_f32 v52, v52, v46, v47
	v_max3_f32 v52, v52, v16, v17
	v_max3_f32 v52, v52, v18, v19
	v_max3_f32 v52, v52, v20, v21
	v_max3_f32 v52, v52, v22, v23
	v_max3_f32 v52, v52, v24, v25
	v_max3_f32 v52, v52, v26, v27
	v_max3_f32 v52, v52, v28, v29
	v_max3_f32 v52, v52, v30, v31
	v_mov_b32_e32 v53, v52
	s_nop 1
	v_permlane32_swap_b32_e32 v52, v53
	v_max_f32_e32 v52, v52, v53
	v_sub_f32_e32 v82, v16, v52
	v_mov_b32_e32 v16, v64
	s_nop 1
	v_permlane32_swap_b32_e32 v64, v16
	v_add_f32_e32 v16, v64, v16
	v_sub_f32_e32 v83, v17, v52
	v_mul_f32_e32 v17, 0x4f800000, v16
	v_cmp_gt_f32_e32 vcc, s65, v16
	v_sub_f32_e32 v84, v18, v52
	v_sub_f32_e32 v85, v19, v52
	v_cndmask_b32_e32 v16, v16, v17, vcc
	v_sqrt_f32_e32 v17, v16
	v_add_f32_e32 v222, 0, v52
	v_sub_f32_e32 v32, v32, v52
	v_sub_f32_e32 v33, v33, v52
	v_add_u32_e32 v18, -1, v17
	v_fma_f32 v19, -v18, v17, v16
	v_cmp_ge_f32_e64 s[0:1], 0, v19
	v_add_u32_e32 v19, 1, v17
	v_sub_f32_e32 v34, v34, v52
	v_cndmask_b32_e64 v18, v17, v18, s[0:1]
	v_fma_f32 v17, -v19, v17, v16
	v_cmp_lt_f32_e64 s[0:1], 0, v17
	v_sub_f32_e32 v35, v35, v52
	v_sub_f32_e32 v36, v36, v52
	v_cndmask_b32_e64 v17, v18, v19, s[0:1]
	v_mul_f32_e32 v18, 0x37800000, v17
	v_cndmask_b32_e32 v17, v17, v18, vcc
	v_cmp_class_f32_e32 vcc, v16, v218
	v_sub_f32_e32 v37, v37, v52
	v_sub_f32_e32 v38, v38, v52
	v_cndmask_b32_e32 v16, v17, v16, vcc
	v_fma_f32 v16, v216, v16, -v222
	v_cmp_ge_f32_e32 vcc, s66, v16
	s_cmp_lg_u64 vcc, exec
	s_cselect_b64 s[0:1], -1, 0
	s_or_b32 s8, s9, s8
	v_sub_f32_e32 v39, v39, v52
	v_sub_f32_e32 v40, v40, v52
	v_sub_f32_e32 v41, v41, v52
	v_sub_f32_e32 v42, v42, v52
	v_sub_f32_e32 v43, v43, v52
	v_sub_f32_e32 v44, v44, v52
	v_sub_f32_e32 v45, v45, v52
	v_sub_f32_e32 v46, v46, v52
	v_sub_f32_e32 v47, v47, v52
	v_xor_b32_e32 v66, 0x80000000, v222
	v_mov_b32_e32 v16, s8
	v_mov_b32_e32 v17, v1
	v_and_b32_e32 v18, 15, v186
	v_mov_b32_e32 v67, v66
	v_mov_b32_e32 v68, v66
	v_mov_b32_e32 v69, v66
	v_mov_b32_e32 v70, v66
	v_mov_b32_e32 v71, v66
	v_mov_b32_e32 v72, v66
	v_mov_b32_e32 v73, v66
	v_mov_b32_e32 v74, v66
	v_mov_b32_e32 v75, v66
	v_mov_b32_e32 v76, v66
	v_mov_b32_e32 v77, v66
	v_mov_b32_e32 v78, v66
	v_mov_b32_e32 v79, v66
	v_mov_b32_e32 v80, v66
	v_mov_b32_e32 v81, v66
	v_exp_f32_e32 v114, v32
	v_exp_f32_e32 v115, v33
	v_exp_f32_e32 v116, v34
	v_exp_f32_e32 v117, v35
	v_exp_f32_e32 v118, v36
	v_exp_f32_e32 v119, v37
	v_exp_f32_e32 v120, v38
	v_exp_f32_e32 v121, v39
	v_exp_f32_e32 v122, v40
	v_exp_f32_e32 v123, v41
	v_exp_f32_e32 v124, v42
	v_exp_f32_e32 v125, v43
	v_exp_f32_e32 v126, v44
	v_exp_f32_e32 v127, v45
	v_exp_f32_e32 v128, v46
	v_exp_f32_e32 v129, v47
	v_mad_i64_i32 v[16:17], s[8:9], v189, s51, v[16:17]
	v_lshlrev_b32_e32 v18, 4, v18
	v_mov_b32_e32 v19, v1
	v_sub_f32_e32 v97, v31, v52
	v_sub_f32_e32 v96, v30, v52
	v_sub_f32_e32 v95, v29, v52
	v_sub_f32_e32 v94, v28, v52
	v_sub_f32_e32 v93, v27, v52
	v_sub_f32_e32 v92, v26, v52
	v_sub_f32_e32 v91, v25, v52
	v_sub_f32_e32 v90, v24, v52
	v_sub_f32_e32 v89, v23, v52
	v_sub_f32_e32 v88, v22, v52
	v_sub_f32_e32 v87, v21, v52
	v_sub_f32_e32 v86, v20, v52
	s_waitcnt vmcnt(0)
; #define SLOAD(k0) do { sr_.vs0 = *(const bf16x8*)(&Vh[(long)((k0) + sr) * LDK + sc]); sr_.vs1 = *(const bf16x8*)(&Vh[(long)((k0) + 32 + sr) * LDK + sc]); \
;     sr_.ks0 = *(const bf16x8*)(&Kh[(long)((k0) + sr) * LDK + sc]); sr_.ks1 = *(const bf16x8*)(&Kh[(long)((k0) + 32 + sr) * LDK + sc]); } while (0)
; #define SWRITE(so) do { *(bf16x8*)(lds + (so) + vst0) = sr_.vs0; *(bf16x8*)(lds + (so) + vst1) = sr_.vs1;          \
;     *(bf16x8*)(lds + (so) + kst0) = sr_.ks0; *(bf16x8*)(lds + (so) + kst1) = sr_.ks1; } while (0)
; #define SWAIT() asm volatile("s_waitcnt vmcnt(0)" ::: "memory")
; __device__ __forceinline__ void attn_item(const bf16_t* __restrict__ Qb, const bf16_t* __restrict__ Kh, const bf16_t* __restrict__ Vh, const bf16_t* __restrict__ Zb, ...
;     ...
;   f32x16 pA0, pA1, pB0, pB1; float alA, alB; VF8 vfa; bf16x8 pa0, pa1, pa2, pa3; const int NT = seq / KVBLK;
;   int s_prev = 0, s_cur = SLOT, s_next = 2 * SLOT;
;   SLOAD(0); SWAIT(); SWRITE(0); __syncthreads();
;   SLOAD(KVBLK);
;   qkt(pA0, pA1, (const bf16_t*)(lds + KOFF), qr, negm, r32, hi); partialSM<true>(pA0, pA1, m_reg, negm, alA);
;   { auto rr = __builtin_amdgcn_permlane32_swap(__float_as_uint(qn2), __float_as_uint(qn2), false, false); qn2 = __uint_as_float(rr[0]) + __uint_as_float(rr[1]); }
;   const bool track = !__all(__builtin_sqrtf(qn2) * kmaxg - m_reg <= 90.f);
;   SWAIT(); SWRITE(SLOT); __syncthreads();
	s_waitcnt vmcnt(3)
	ds_write_b128 v108, v[48:51] offset:32768
	s_waitcnt vmcnt(1)
	ds_write_b128 v109, v[98:101] offset:32768
	ds_write_b128 v112, v[60:63] offset:49152
	s_waitcnt vmcnt(0)
	ds_write_b128 v113, v[102:105] offset:49152
	v_bitop3_b32 v240, v59, v221, v190 bitop3:0xde
	v_lshl_add_u64 v[16:17], v[16:17], 0, v[18:19]
	v_mov_b64_e32 v[64:65], v[14:15]
	v_mov_b64_e32 v[48:49], v[14:15]
	v_mov_b64_e32 v[32:33], v[14:15]
	v_lshl_add_u64 v[214:215], s[20:21], 0, v[16:17]
	v_mov_b64_e32 v[62:63], v[12:13]
	v_mov_b64_e32 v[60:61], v[10:11]
	v_mov_b64_e32 v[58:59], v[8:9]
	v_mov_b64_e32 v[56:57], v[6:7]
	v_mov_b64_e32 v[54:55], v[4:5]
	v_mov_b64_e32 v[52:53], v[2:3]
	v_mov_b64_e32 v[50:51], v[0:1]
	v_mov_b64_e32 v[46:47], v[12:13]
	v_mov_b64_e32 v[44:45], v[10:11]
	v_mov_b64_e32 v[42:43], v[8:9]
	v_mov_b64_e32 v[40:41], v[6:7]
	v_mov_b64_e32 v[38:39], v[4:5]
	v_mov_b64_e32 v[36:37], v[2:3]
	v_mov_b64_e32 v[34:35], v[0:1]
	v_mov_b64_e32 v[30:31], v[12:13]
	v_mov_b64_e32 v[28:29], v[10:11]
	v_mov_b64_e32 v[26:27], v[8:9]
	v_mov_b64_e32 v[24:25], v[6:7]
	v_mov_b64_e32 v[22:23], v[4:5]
	v_mov_b64_e32 v[20:21], v[2:3]
	v_mov_b64_e32 v[18:19], v[0:1]
	v_mov_b64_e32 v[16:17], v[14:15]
	v_mov_b64_e32 v[14:15], v[12:13]
	v_mov_b64_e32 v[12:13], v[10:11]
	v_mov_b64_e32 v[10:11], v[8:9]
	v_mov_b64_e32 v[8:9], v[6:7]
	v_mov_b64_e32 v[6:7], v[4:5]
	v_mov_b64_e32 v[4:5], v[2:3]
	v_mov_b64_e32 v[2:3], v[0:1]
	v_add_co_u32_e32 v248, vcc, s67, v214
	s_nop 1
	v_addc_co_u32_e32 v249, vcc, -1, v215, vcc
	v_add_co_u32_e32 v250, vcc, s68, v214
	s_nop 1
	v_addc_co_u32_e32 v251, vcc, -1, v215, vcc
	global_load_dwordx4 v[180:183], v[248:249], off
	global_load_dwordx4 v[184:187], v[248:249], off offset:-512
	global_load_dwordx4 v[192:195], v[250:251], off
	global_load_dwordx4 v[188:191], v[250:251], off offset:-512
	v_add_u32_e32 v252, 0x10000, v228
	v_add_u32_e32 v253, 0x10000, v229
	v_add_u32_e32 v254, 0x10000, v231
	v_add_u32_e32 v255, 0x10000, v232
	s_waitcnt vmcnt(0)
	ds_write_b128 v252, v[180:183]
	ds_write_b128 v253, v[192:195]
	ds_write_b128 v254, v[184:187] offset:16384
	ds_write_b128 v255, v[188:191] offset:16384
	v_mbcnt_lo_u32_b32 v248, -1, 0
	v_mbcnt_hi_u32_b32 v248, -1, v248
	s_lshr_b32 s79, s33, 6
	s_lshl_b32 s100, s79, 10
	s_lshl_b32 s101, s79, 11
	s_mov_b32 s76, 0x82000
	s_mov_b32 s77, 0
	v_and_b32_e32 v249, 15, v248
	v_lshrrev_b32_e32 v250, 4, v248
	v_lshl_add_u32 v250, s79, 2, v250
	v_and_b32_e32 v251, 15, v250
	v_xor_b32_e32 v251, v249, v251
	v_sub_u32_e32 v251, v251, v249
	v_lshlrev_b32_e32 v251, 4, v251
	v_add_u32_e32 v252, 0xfffbee00, v251
	v_ashrrev_i32_e32 v253, 31, v252
	v_and_b32_e32 v254, 31, v248
	v_lshrrev_b32_e32 v254, 2, v254
	v_lshl_add_u32 v254, s79, 3, v254
	v_sub_u32_e32 v254, v254, v250
	v_add_u32_e32 v254, 0xffffffe0, v254
	v_mov_b32_e32 v255, 0x2080
	v_mul_lo_u32 v254, v254, v255
	v_lshrrev_b32_e32 v255, 5, v248
	v_lshl_add_u32 v254, v255, 6, v254
	v_and_b32_e32 v255, 3, v248
	v_lshl_add_u32 v254, v255, 4, v254
	v_lshlrev_b32_e32 v255, 4, v249
	v_sub_u32_e32 v254, v254, v255
	s_waitcnt lgkmcnt(0)
	v_lshl_add_u64 v[180:181], v[214:215], 0, v[252:253]
	v_ashrrev_i32_e32 v255, 31, v254
	v_add_co_u32_e32 v182, vcc, 0x41000, v180
	s_nop 1
	v_addc_co_u32_e32 v183, vcc, 0, v181, vcc
	v_lshl_add_u64 v[214:215], v[214:215], 0, v[254:255]
	v_readfirstlane_b32 s82, v180
	v_readfirstlane_b32 s83, v181
	s_sub_u32 s82, s82, 0x400000
	s_subb_u32 s83, s83, 0
	v_subrev_u32_e32 v180, s82, v180
	v_subrev_u32_e32 v182, s82, v182
	v_subrev_u32_e32 v214, s82, v214
	s_mov_b32 s96, 0x8000
	s_mov_b32 s8, 0
	s_cmp_ge_u32 s33, 0x100
	s_cbranch_scc1 .Lh2_pro
	s_barrier

; #define SBAR() __builtin_amdgcn_sched_barrier(0)
; #define PVE_M(OD, PA, L, H, IDX) do { OD = __builtin_amdgcn_mfma_f32_32x32x16_bf16(PA, PKV(L, H), OD, 0, 0, 0); SBAR(); p[IDX] = __builtin_amdgcn_exp2f(p[IDX]); asm volatile("" : "+v"(p)); SBAR(); } while (0)
; __device__ __forceinline__ void pv_exp(f32x16* o, int vb, bf16x8 pa0, bf16x8 pa1, bf16x8 pa2, bf16x8 pa3, f32x16& p, VF8& fa) {
;   VF8 fb;
;   asm volatile("s_waitcnt lgkmcnt(0)" ::: "memory"); SBAR();
;   PVE_M(o[0], pa0, fa.l0, fa.h0, 0); PVE_M(o[0], pa1, fa.l1, fa.h1, 1); vf8_read<1>(fb, vb); SBAR(); PVE_M(o[0], pa2, fa.l2, fa.h2, 2); PVE_M(o[0], pa3, fa.l3, fa.h3, 3);
;   asm volatile("s_waitcnt lgkmcnt(0)" ::: "memory"); SBAR();
;   PVE_M(o[1], pa0, fb.l0, fb.h0, 4); PVE_M(o[1], pa1, fb.l1, fb.h1, 5); vf8_read<2>(fa, vb); SBAR(); PVE_M(o[1], pa2, fb.l2, fb.h2, 6); PVE_M(o[1], pa3, fb.l3, fb.h3, 7);
;   asm volatile("s_waitcnt lgkmcnt(0)" ::: "memory"); SBAR();
;   PVE_M(o[2], pa0, fa.l0, fa.h0, 8); PVE_M(o[2], pa1, fa.l1, fa.h1, 9); vf8_read<3>(fb, vb); SBAR(); PVE_M(o[2], pa2, fa.l2, fa.h2, 10); PVE_M(o[2], pa3, fa.l3, fa.h3, 11);
;   asm volatile("s_waitcnt lgkmcnt(0)" ::: "memory"); SBAR();
;   PVE_M(o[3], pa0, fb.l0, fb.h0, 12); PVE_M(o[3], pa1, fb.l1, fb.h1, 13); PVE_M(o[3], pa2, fb.l2, fb.h2, 14); PVE_M(o[3], pa3, fb.l3, fb.h3, 15);
; }
.LBB0_457:
	s_waitcnt vmcnt(0)
	s_barrier
	s_waitcnt lgkmcnt(0)
	v_mfma_f32_32x32x16_bf16 v[50:65], v[196:199], v[94:97], v[50:65]
	v_exp_f32_e32 v132, v132
	v_mfma_f32_32x32x16_bf16 v[50:65], v[204:207], v[90:93], v[50:65]
	v_exp_f32_e32 v133, v133
	ds_read_b64_tr_b16 v[90:91], v0 offset:0x200
	ds_read_b64_tr_b16 v[92:93], v0 offset:0xa00
	ds_read_b64_tr_b16 v[94:95], v0 offset:0x1200
	ds_read_b64_tr_b16 v[96:97], v0 offset:0x1a00
	ds_read_b64_tr_b16 v[114:115], v0 offset:0x2200
	ds_read_b64_tr_b16 v[116:117], v0 offset:0x2a00
	ds_read_b64_tr_b16 v[118:119], v0 offset:0x3200
	ds_read_b64_tr_b16 v[120:121], v0 offset:0x3a00
	v_mfma_f32_32x32x16_bf16 v[50:65], v[200:203], v[86:89], v[50:65]
	v_exp_f32_e32 v134, v134
	v_mfma_f32_32x32x16_bf16 v[50:65], v[208:211], v[82:85], v[50:65]
	v_exp_f32_e32 v135, v135
	s_waitcnt lgkmcnt(0)
	v_mfma_f32_32x32x16_bf16 v[34:49], v[196:199], v[90:93], v[34:49]
	v_exp_f32_e32 v136, v136
	s_add_i32 s79, s98, s100
	s_add_i32 m0, s79, 0x4000
	s_add_i32 s79, s79, 0x6000
	global_load_lds_dwordx4 v180, s[82:83]
	v_mfma_f32_32x32x16_bf16 v[34:49], v[204:207], v[94:97], v[34:49]
	v_exp_f32_e32 v137, v137
	s_mov_b32 m0, s79
	s_add_i32 s79, s98, s101
	global_load_lds_dwordx4 v182, s[82:83]
	ds_read_b64_tr_b16 v[82:83], v0 offset:0x400
	ds_read_b64_tr_b16 v[84:85], v0 offset:0xc00
	ds_read_b64_tr_b16 v[86:87], v0 offset:0x1400
	ds_read_b64_tr_b16 v[88:89], v0 offset:0x1c00
	ds_read_b64_tr_b16 v[90:91], v0 offset:0x2400
	ds_read_b64_tr_b16 v[92:93], v0 offset:0x2c00
	ds_read_b64_tr_b16 v[94:95], v0 offset:0x3400
	ds_read_b64_tr_b16 v[96:97], v0 offset:0x3c00
	v_mfma_f32_32x32x16_bf16 v[34:49], v[200:203], v[114:117], v[34:49]
	v_exp_f32_e32 v138, v138
	s_mov_b32 m0, s79
	s_add_i32 s79, s79, 0x380
	global_load_lds_dwordx4 v214, s[82:83]
	v_mfma_f32_32x32x16_bf16 v[34:49], v[208:211], v[118:121], v[34:49]
	v_exp_f32_e32 v139, v139
	s_mov_b32 m0, s79
	s_nop 0
	global_load_lds_dwordx4 v214, s[82:83] offset:128
	s_add_u32 s82, s82, s76
	s_addc_u32 s83, s83, s77
	s_waitcnt lgkmcnt(0)
	v_mfma_f32_32x32x16_bf16 v[18:33], v[196:199], v[82:85], v[18:33]
	v_exp_f32_e32 v140, v140
	v_mfma_f32_32x32x16_bf16 v[18:33], v[204:207], v[86:89], v[18:33]
	v_exp_f32_e32 v141, v141
	ds_read_b64_tr_b16 v[82:83], v0 offset:0x600
	ds_read_b64_tr_b16 v[84:85], v0 offset:0xe00
	ds_read_b64_tr_b16 v[86:87], v0 offset:0x1600
	ds_read_b64_tr_b16 v[88:89], v0 offset:0x1e00
	ds_read_b64_tr_b16 v[114:115], v0 offset:0x2600
	ds_read_b64_tr_b16 v[116:117], v0 offset:0x2e00
	ds_read_b64_tr_b16 v[118:119], v0 offset:0x3600
	ds_read_b64_tr_b16 v[120:121], v0 offset:0x3e00
	v_mfma_f32_32x32x16_bf16 v[18:33], v[200:203], v[90:93], v[18:33]
	v_exp_f32_e32 v142, v142
	v_mfma_f32_32x32x16_bf16 v[18:33], v[208:211], v[94:97], v[18:33]
	v_exp_f32_e32 v143, v143
	s_waitcnt lgkmcnt(0)
	v_mfma_f32_32x32x16_bf16 v[2:17], v[196:199], v[82:85], v[2:17]
	v_exp_f32_e32 v144, v144
	v_mfma_f32_32x32x16_bf16 v[2:17], v[204:207], v[86:89], v[2:17]
	v_exp_f32_e32 v145, v145
	v_mfma_f32_32x32x16_bf16 v[2:17], v[200:203], v[114:117], v[2:17]
	v_exp_f32_e32 v146, v146
	v_mfma_f32_32x32x16_bf16 v[2:17], v[208:211], v[118:121], v[2:17]
	v_exp_f32_e32 v147, v147
	v_cmp_gt_f32_e32 vcc, 1.0, v130
	s_cbranch_vccz .LBB0_461
	s_and_saveexec_b64 s[36:37], s[6:7]
	ds_write_b32 v220, v130 offset:128
	s_or_b64 exec, exec, s[36:37]
	s_waitcnt lgkmcnt(0)
	v_add_u32_e32 v94, v213, v212
	ds_read_b128 v[82:85], v94 offset:224
	ds_read_b128 v[86:89], v94 offset:192
	ds_read_b128 v[90:93], v94 offset:160
	ds_read_b128 v[94:97], v94 offset:128
	s_waitcnt lgkmcnt(3)
	v_pk_mul_f32 v[62:63], v[62:63], v[82:83]
	s_waitcnt lgkmcnt(2)
	v_pk_mul_f32 v[58:59], v[58:59], v[86:87]
	s_waitcnt lgkmcnt(1)
	v_pk_mul_f32 v[54:55], v[54:55], v[90:91]
	v_pk_mul_f32 v[64:65], v[64:65], v[84:85]
	v_pk_mul_f32 v[60:61], v[60:61], v[88:89]
	v_pk_mul_f32 v[56:57], v[56:57], v[92:93]
	s_waitcnt lgkmcnt(0)
	v_pk_mul_f32 v[52:53], v[52:53], v[96:97]
	v_pk_mul_f32 v[50:51], v[50:51], v[94:95]
	v_pk_mul_f32 v[46:47], v[46:47], v[82:83]
	v_pk_mul_f32 v[42:43], v[42:43], v[86:87]
	v_pk_mul_f32 v[38:39], v[38:39], v[90:91]
	v_pk_mul_f32 v[48:49], v[48:49], v[84:85]
	v_pk_mul_f32 v[44:45], v[44:45], v[88:89]
	v_pk_mul_f32 v[40:41], v[40:41], v[92:93]
	v_pk_mul_f32 v[36:37], v[36:37], v[96:97]
	v_pk_mul_f32 v[34:35], v[34:35], v[94:95]
	v_pk_mul_f32 v[30:31], v[30:31], v[82:83]
	v_pk_mul_f32 v[26:27], v[26:27], v[86:87]
	v_pk_mul_f32 v[22:23], v[22:23], v[90:91]
	v_pk_mul_f32 v[32:33], v[32:33], v[84:85]
	v_pk_mul_f32 v[28:29], v[28:29], v[88:89]
	v_pk_mul_f32 v[24:25], v[24:25], v[92:93]
	v_pk_mul_f32 v[20:21], v[20:21], v[96:97]
	v_pk_mul_f32 v[18:19], v[18:19], v[94:95]
	v_pk_mul_f32 v[14:15], v[14:15], v[82:83]
	v_pk_mul_f32 v[10:11], v[10:11], v[86:87]
	v_pk_mul_f32 v[6:7], v[6:7], v[90:91]
	v_pk_mul_f32 v[16:17], v[16:17], v[84:85]
	v_pk_mul_f32 v[12:13], v[12:13], v[88:89]
	v_pk_mul_f32 v[8:9], v[8:9], v[92:93]
	v_pk_mul_f32 v[4:5], v[4:5], v[96:97]
	v_pk_mul_f32 v[2:3], v[2:3], v[94:95]

; #define SBAR() __builtin_amdgcn_sched_barrier(0)
; #define PVE_M(OD, PA, L, H, IDX) do { OD = __builtin_amdgcn_mfma_f32_32x32x16_bf16(PA, PKV(L, H), OD, 0, 0, 0); SBAR(); p[IDX] = __builtin_amdgcn_exp2f(p[IDX]); asm volatile("" : "+v"(p)); SBAR(); } while (0)
; __device__ __forceinline__ void pv_exp(f32x16* o, int vb, bf16x8 pa0, bf16x8 pa1, bf16x8 pa2, bf16x8 pa3, f32x16& p, VF8& fa) {
;   VF8 fb;
;   asm volatile("s_waitcnt lgkmcnt(0)" ::: "memory"); SBAR();
;   PVE_M(o[0], pa0, fa.l0, fa.h0, 0); PVE_M(o[0], pa1, fa.l1, fa.h1, 1); vf8_read<1>(fb, vb); SBAR(); PVE_M(o[0], pa2, fa.l2, fa.h2, 2); PVE_M(o[0], pa3, fa.l3, fa.h3, 3);
;   asm volatile("s_waitcnt lgkmcnt(0)" ::: "memory"); SBAR();
;   PVE_M(o[1], pa0, fb.l0, fb.h0, 4); PVE_M(o[1], pa1, fb.l1, fb.h1, 5); vf8_read<2>(fa, vb); SBAR(); PVE_M(o[1], pa2, fb.l2, fb.h2, 6); PVE_M(o[1], pa3, fb.l3, fb.h3, 7);
;   asm volatile("s_waitcnt lgkmcnt(0)" ::: "memory"); SBAR();
;   PVE_M(o[2], pa0, fa.l0, fa.h0, 8); PVE_M(o[2], pa1, fa.l1, fa.h1, 9); vf8_read<3>(fb, vb); SBAR(); PVE_M(o[2], pa2, fa.l2, fa.h2, 10); PVE_M(o[2], pa3, fa.l3, fa.h3, 11);
;   asm volatile("s_waitcnt lgkmcnt(0)" ::: "memory"); SBAR();
;   PVE_M(o[3], pa0, fb.l0, fb.h0, 12); PVE_M(o[3], pa1, fb.l1, fb.h1, 13); PVE_M(o[3], pa2, fb.l2, fb.h2, 14); PVE_M(o[3], pa3, fb.l3, fb.h3, 15);
; }
.LBB0_463:
	s_waitcnt vmcnt(0)
	s_barrier
	s_waitcnt lgkmcnt(0)
	v_mfma_f32_32x32x16_bf16 v[50:65], v[132:135], v[144:147], v[50:65]
	v_exp_f32_e32 v114, v114
	v_mfma_f32_32x32x16_bf16 v[50:65], v[136:139], v[106:109], v[50:65]
	v_exp_f32_e32 v115, v115
	ds_read_b64_tr_b16 v[106:107], v203 offset:0x200
	ds_read_b64_tr_b16 v[108:109], v203 offset:0xa00
	ds_read_b64_tr_b16 v[144:145], v203 offset:0x1200
	ds_read_b64_tr_b16 v[146:147], v203 offset:0x1a00
	ds_read_b64_tr_b16 v[204:205], v203 offset:0x2200
	ds_read_b64_tr_b16 v[206:207], v203 offset:0x2a00
	ds_read_b64_tr_b16 v[208:209], v203 offset:0x3200
	ds_read_b64_tr_b16 v[210:211], v203 offset:0x3a00
	v_mfma_f32_32x32x16_bf16 v[50:65], v[196:199], v[102:105], v[50:65]
	v_exp_f32_e32 v116, v116
	v_mfma_f32_32x32x16_bf16 v[50:65], v[140:143], v[98:101], v[50:65]
	v_exp_f32_e32 v117, v117
	s_waitcnt lgkmcnt(0)
	v_mfma_f32_32x32x16_bf16 v[34:49], v[132:135], v[106:109], v[34:49]
	v_exp_f32_e32 v118, v118
	s_add_i32 s79, s97, s100
	s_add_i32 m0, s79, 0x4000
	s_add_i32 s79, s79, 0x6000
	global_load_lds_dwordx4 v180, s[82:83]
	v_mfma_f32_32x32x16_bf16 v[34:49], v[136:139], v[144:147], v[34:49]
	v_exp_f32_e32 v119, v119
	s_mov_b32 m0, s79
	s_add_i32 s79, s97, s101
	global_load_lds_dwordx4 v182, s[82:83]
	ds_read_b64_tr_b16 v[98:99], v203 offset:0x400
	ds_read_b64_tr_b16 v[100:101], v203 offset:0xc00
	ds_read_b64_tr_b16 v[102:103], v203 offset:0x1400
	ds_read_b64_tr_b16 v[104:105], v203 offset:0x1c00
	ds_read_b64_tr_b16 v[106:107], v203 offset:0x2400
	ds_read_b64_tr_b16 v[108:109], v203 offset:0x2c00
	ds_read_b64_tr_b16 v[144:145], v203 offset:0x3400
	ds_read_b64_tr_b16 v[146:147], v203 offset:0x3c00
	v_mfma_f32_32x32x16_bf16 v[34:49], v[196:199], v[204:207], v[34:49]
	v_exp_f32_e32 v120, v120
	s_mov_b32 m0, s79
	s_add_i32 s79, s79, 0x380
	global_load_lds_dwordx4 v214, s[82:83]
	v_mfma_f32_32x32x16_bf16 v[34:49], v[140:143], v[208:211], v[34:49]
	v_exp_f32_e32 v121, v121
	s_mov_b32 m0, s79
	s_nop 0
	global_load_lds_dwordx4 v214, s[82:83] offset:128
	s_add_u32 s82, s82, s76
	s_addc_u32 s83, s83, s77
	s_waitcnt lgkmcnt(0)
	v_mfma_f32_32x32x16_bf16 v[18:33], v[132:135], v[98:101], v[18:33]
	v_exp_f32_e32 v122, v122
	v_mfma_f32_32x32x16_bf16 v[18:33], v[136:139], v[102:105], v[18:33]
	v_exp_f32_e32 v123, v123
	ds_read_b64_tr_b16 v[98:99], v203 offset:0x600
	ds_read_b64_tr_b16 v[100:101], v203 offset:0xe00
	ds_read_b64_tr_b16 v[102:103], v203 offset:0x1600
	ds_read_b64_tr_b16 v[104:105], v203 offset:0x1e00
	ds_read_b64_tr_b16 v[204:205], v203 offset:0x2600
	ds_read_b64_tr_b16 v[206:207], v203 offset:0x2e00
	ds_read_b64_tr_b16 v[208:209], v203 offset:0x3600
	ds_read_b64_tr_b16 v[210:211], v203 offset:0x3e00
	v_mfma_f32_32x32x16_bf16 v[18:33], v[196:199], v[106:109], v[18:33]
	v_exp_f32_e32 v124, v124
	v_mfma_f32_32x32x16_bf16 v[18:33], v[140:143], v[144:147], v[18:33]
	v_exp_f32_e32 v125, v125
	s_waitcnt lgkmcnt(0)
	v_mfma_f32_32x32x16_bf16 v[2:17], v[132:135], v[98:101], v[2:17]
	v_exp_f32_e32 v126, v126
	v_mfma_f32_32x32x16_bf16 v[2:17], v[136:139], v[102:105], v[2:17]
	v_exp_f32_e32 v127, v127
	v_mfma_f32_32x32x16_bf16 v[2:17], v[196:199], v[204:207], v[2:17]
	v_exp_f32_e32 v128, v128
	v_mfma_f32_32x32x16_bf16 v[2:17], v[140:143], v[208:211], v[2:17]
	v_exp_f32_e32 v129, v129
	v_cmp_gt_f32_e32 vcc, 1.0, v200
	s_cbranch_vccz .LBB0_467
	s_and_saveexec_b64 s[36:37], s[6:7]
	ds_write_b32 v220, v200 offset:128
	s_or_b64 exec, exec, s[36:37]
	s_waitcnt lgkmcnt(0)
	v_add_u32_e32 v110, v213, v212
	ds_read_b128 v[98:101], v110 offset:224
	ds_read_b128 v[102:105], v110 offset:192
	ds_read_b128 v[106:109], v110 offset:160
	ds_read_b128 v[132:135], v110 offset:128
	s_waitcnt lgkmcnt(3)
	v_pk_mul_f32 v[62:63], v[62:63], v[98:99]
	s_waitcnt lgkmcnt(2)
	v_pk_mul_f32 v[58:59], v[58:59], v[102:103]
	s_waitcnt lgkmcnt(1)
	v_pk_mul_f32 v[54:55], v[54:55], v[106:107]
	v_pk_mul_f32 v[64:65], v[64:65], v[100:101]
	v_pk_mul_f32 v[60:61], v[60:61], v[104:105]
	v_pk_mul_f32 v[56:57], v[56:57], v[108:109]
	s_waitcnt lgkmcnt(0)
	v_pk_mul_f32 v[52:53], v[52:53], v[134:135]
	v_pk_mul_f32 v[50:51], v[50:51], v[132:133]
	v_pk_mul_f32 v[46:47], v[46:47], v[98:99]
	v_pk_mul_f32 v[42:43], v[42:43], v[102:103]
	v_pk_mul_f32 v[38:39], v[38:39], v[106:107]
	v_pk_mul_f32 v[48:49], v[48:49], v[100:101]
	v_pk_mul_f32 v[44:45], v[44:45], v[104:105]
	v_pk_mul_f32 v[40:41], v[40:41], v[108:109]
	v_pk_mul_f32 v[36:37], v[36:37], v[134:135]
	v_pk_mul_f32 v[34:35], v[34:35], v[132:133]
	v_pk_mul_f32 v[30:31], v[30:31], v[98:99]
	v_pk_mul_f32 v[26:27], v[26:27], v[102:103]
	v_pk_mul_f32 v[22:23], v[22:23], v[106:107]
	v_pk_mul_f32 v[32:33], v[32:33], v[100:101]
	v_pk_mul_f32 v[28:29], v[28:29], v[104:105]
	v_pk_mul_f32 v[24:25], v[24:25], v[108:109]
	v_pk_mul_f32 v[20:21], v[20:21], v[134:135]
	v_pk_mul_f32 v[18:19], v[18:19], v[132:133]
	v_pk_mul_f32 v[14:15], v[14:15], v[98:99]
	v_pk_mul_f32 v[10:11], v[10:11], v[102:103]
	v_pk_mul_f32 v[6:7], v[6:7], v[106:107]
	v_pk_mul_f32 v[16:17], v[16:17], v[100:101]
	v_pk_mul_f32 v[12:13], v[12:13], v[104:105]
	v_pk_mul_f32 v[8:9], v[8:9], v[108:109]
	v_pk_mul_f32 v[4:5], v[4:5], v[134:135]
	v_pk_mul_f32 v[2:3], v[2:3], v[132:133]

; #define SBAR() __builtin_amdgcn_sched_barrier(0)
; __device__ __forceinline__ unsigned cvtpk(float lo, float hi) { unsigned r; asm volatile("v_cvt_pk_bf16_f32 %0, %1, %2" : "=v"(r) : "v"(lo), "v"(hi)); return r; }
; __device__ __forceinline__ void qkt_fin(f32x16& n0, f32x16& n1, const bf16_t* Ks, const bf16x8* qr, const f32x16& negm, int r32, int hi, ...
;   float psa = 0.f, psb = 0.f; u32x4 wa, wb, wc, wd;
;     ...
; #pragma unroll
;   for (int d0 = 0; d0 < 8; ++d0) { int cb = (d0 * 16 + hi * 8) * 2;
;     bf16x8 b0 = *reinterpret_cast<const bf16x8*>((const char*)Ks + KSWZ(r32, cb));
;     bf16x8 b1 = *reinterpret_cast<const bf16x8*>((const char*)Ks + KSWZ(32 + r32, cb));
;     SBAR(); if (d0 == 0) n0 = __builtin_amdgcn_mfma_f32_32x32x16_bf16(b0, qr[0], negm, 0, 0, 0); else n0 = __builtin_amdgcn_mfma_f32_32x32x16_bf16(b0, qr[d0], n0, 0, 0, 0);
;     SBAR(); QF_CHUNK(2 * d0); SBAR();
;     if (d0 == 0) n1 = __builtin_amdgcn_mfma_f32_32x32x16_bf16(b1, qr[0], negm, 0, 0, 0); else n1 = __builtin_amdgcn_mfma_f32_32x32x16_bf16(b1, qr[d0], n1, 0, 0, 0);
;     SBAR(); QF_CHUNK(2 * d0 + 1); SBAR();
;     if (d0 == 7) { vf8_read<0>(vf0, vbv); SBAR(); } }
;     ...
;   psb += P1[15]; wd[3] = cvtpk(P1[14], P1[15]);
;   l_reg = l_reg * alpha + (psa + psb);
;   pa0 = *reinterpret_cast<bf16x8*>(&wa); pa1 = *reinterpret_cast<bf16x8*>(&wb); pa2 = *reinterpret_cast<bf16x8*>(&wc); pa3 = *reinterpret_cast<bf16x8*>(&wd);
; }
.Lh2_pro:
	s_sub_u32 s82, s82, 0x82000
	s_subb_u32 s83, s83, 0
	s_barrier
.Lh2_453:
	s_setprio 1
	s_add_i32 s97, s96, 0xffff8000
	s_xor_b32 s98, s96, 0x10000
	s_add_i32 s99, s96, 0x8000
	s_and_b32 s99, s99, 0x18000
	v_add_u32_e32 v196, s96, v236
	ds_read_b128 v[98:101], v196 offset:16384
	ds_read_b128 v[196:199], v196 offset:24576
	v_add_u32_e32 v252, s96, v237
	ds_read_b128 v[248:251], v252 offset:16384
	ds_read_b128 v[252:255], v252 offset:24576
	v_add_u32_e32 v0, s97, v235
	s_waitcnt lgkmcnt(3)
	v_mfma_f32_32x32x16_bf16 v[132:147], v[98:101], v[152:155], v[66:81]
	v_exp_f32_e32 v82, v82
	s_waitcnt lgkmcnt(2)
	v_mfma_f32_32x32x16_bf16 v[98:113], v[196:199], v[152:155], v[66:81]
	v_exp_f32_e32 v83, v83
	v_add_f32_e32 v245, v115, v114
	v_cvt_pk_bf16_f32 v196, v114, v115
	v_add_u32_e32 v206, s96, v238
	ds_read_b128 v[202:205], v206 offset:16384
	ds_read_b128 v[206:209], v206 offset:24576
	s_waitcnt lgkmcnt(3)
	v_mfma_f32_32x32x16_bf16 v[132:147], v[248:251], v[160:163], v[132:147]
	v_exp_f32_e32 v84, v84
	v_add_f32_e32 v245, v116, v245
	v_add_f32_e32 v246, v82, v83
	s_waitcnt lgkmcnt(2)
	v_mfma_f32_32x32x16_bf16 v[98:113], v[252:255], v[160:163], v[98:113]
	v_exp_f32_e32 v85, v85
	v_add_f32_e32 v245, v117, v245
	v_add_f32_e32 v246, v246, v84
	v_cvt_pk_bf16_f32 v197, v116, v117
	v_cvt_pk_bf16_f32 v200, v82, v83
	v_add_u32_e32 v252, s96, v239
	ds_read_b128 v[248:251], v252 offset:16384
	ds_read_b128 v[252:255], v252 offset:24576
	s_add_i32 s79, s99, s100
	s_add_i32 m0, s79, 0x4000
	s_add_i32 s79, s79, 0x6000
	global_load_lds_dwordx4 v180, s[82:83]
	s_waitcnt lgkmcnt(3)
	v_mfma_f32_32x32x16_bf16 v[132:147], v[202:205], v[148:151], v[132:147]
	v_exp_f32_e32 v86, v86
	v_add_f32_e32 v245, v118, v245
	v_add_f32_e32 v246, v246, v85
	s_waitcnt lgkmcnt(2)
	v_mfma_f32_32x32x16_bf16 v[98:113], v[206:209], v[148:151], v[98:113]
	v_exp_f32_e32 v87, v87
	v_add_f32_e32 v245, v119, v245
	v_add_f32_e32 v246, v246, v86
	v_cvt_pk_bf16_f32 v198, v118, v119
	v_cvt_pk_bf16_f32 v201, v84, v85
	v_add_u32_e32 v208, s96, v240
	ds_read_b128 v[204:207], v208 offset:16384
	ds_read_b128 v[208:211], v208 offset:24576
	s_mov_b32 m0, s79
	s_add_i32 s79, s99, s101
	global_load_lds_dwordx4 v182, s[82:83]
	s_waitcnt lgkmcnt(3)
	v_mfma_f32_32x32x16_bf16 v[132:147], v[248:251], v[156:159], v[132:147]
	v_exp_f32_e32 v88, v88
	v_add_f32_e32 v245, v120, v245
	v_add_f32_e32 v246, v246, v87
	s_waitcnt lgkmcnt(2)
	v_mfma_f32_32x32x16_bf16 v[98:113], v[252:255], v[156:159], v[98:113]
	v_exp_f32_e32 v89, v89
	v_add_f32_e32 v245, v121, v245
	v_add_f32_e32 v246, v246, v88
	v_cvt_pk_bf16_f32 v199, v120, v121
	v_cvt_pk_bf16_f32 v202, v86, v87
	v_add_u32_e32 v252, s96, v241
	ds_read_b128 v[248:251], v252 offset:16384
	ds_read_b128 v[252:255], v252 offset:24576
	s_mov_b32 m0, s79
	s_add_i32 s79, s79, 0x380
	global_load_lds_dwordx4 v214, s[82:83]
	s_waitcnt lgkmcnt(3)
	v_mfma_f32_32x32x16_bf16 v[132:147], v[204:207], v[168:171], v[132:147]
	v_exp_f32_e32 v90, v90
	v_add_f32_e32 v245, v122, v245
	v_add_f32_e32 v246, v246, v89
	s_waitcnt lgkmcnt(2)
	v_mfma_f32_32x32x16_bf16 v[98:113], v[208:211], v[168:171], v[98:113]
	v_exp_f32_e32 v91, v91
	v_add_f32_e32 v245, v123, v245
	v_add_f32_e32 v246, v246, v90
	v_cvt_pk_bf16_f32 v204, v122, v123
	v_cvt_pk_bf16_f32 v203, v88, v89
	v_add_u32_e32 v118, s96, v242
	ds_read_b128 v[114:117], v118 offset:16384
	ds_read_b128 v[118:121], v118 offset:24576
	s_mov_b32 m0, s79
	s_nop 0
	global_load_lds_dwordx4 v214, s[82:83] offset:128
	s_add_u32 s82, s82, s76
	s_addc_u32 s83, s83, s77
	s_waitcnt lgkmcnt(3)
	v_mfma_f32_32x32x16_bf16 v[132:147], v[248:251], v[176:179], v[132:147]
	v_exp_f32_e32 v92, v92
	v_add_f32_e32 v245, v124, v245
	v_add_f32_e32 v246, v246, v91
	s_waitcnt lgkmcnt(2)
	v_mfma_f32_32x32x16_bf16 v[98:113], v[252:255], v[176:179], v[98:113]
	v_exp_f32_e32 v93, v93
	v_add_f32_e32 v245, v125, v245
	v_add_f32_e32 v246, v246, v92
	v_cvt_pk_bf16_f32 v205, v124, v125
	v_cvt_pk_bf16_f32 v208, v90, v91
	v_add_u32_e32 v252, s96, v243
	ds_read_b128 v[248:251], v252 offset:16384
	ds_read_b128 v[252:255], v252 offset:24576
	s_waitcnt lgkmcnt(3)
	v_mfma_f32_32x32x16_bf16 v[132:147], v[114:117], v[164:167], v[132:147]
	v_exp_f32_e32 v94, v94
	v_add_f32_e32 v245, v126, v245
	v_add_f32_e32 v246, v246, v93
	s_waitcnt lgkmcnt(2)
	v_mfma_f32_32x32x16_bf16 v[98:113], v[118:121], v[164:167], v[98:113]
	v_exp_f32_e32 v95, v95
	v_add_f32_e32 v245, v127, v245
	v_add_f32_e32 v246, v246, v94
	v_cvt_pk_bf16_f32 v206, v126, v127
	v_cvt_pk_bf16_f32 v209, v92, v93
	s_waitcnt lgkmcnt(1)
	v_mfma_f32_32x32x16_bf16 v[132:147], v[248:251], v[172:175], v[132:147]
	v_exp_f32_e32 v96, v96
	v_add_f32_e32 v245, v128, v245
	v_add_f32_e32 v246, v246, v95
	s_waitcnt lgkmcnt(0)
	v_mfma_f32_32x32x16_bf16 v[98:113], v[252:255], v[172:175], v[98:113]
	v_exp_f32_e32 v97, v97
	v_add_f32_e32 v245, v129, v245
	v_add_f32_e32 v246, v246, v96
	v_cvt_pk_bf16_f32 v207, v128, v129
	v_cvt_pk_bf16_f32 v210, v94, v95
	v_mov_b32_e32 v131, v97
	v_cvt_pk_bf16_f32 v211, v96, v97
	ds_read_b64_tr_b16 v[94:95], v0 offset:0
	ds_read_b64_tr_b16 v[96:97], v0 offset:2048
	ds_read_b64_tr_b16 v[90:91], v0 offset:4096
	ds_read_b64_tr_b16 v[92:93], v0 offset:6144
	ds_read_b64_tr_b16 v[86:87], v0 offset:8192
	ds_read_b64_tr_b16 v[88:89], v0 offset:10240
	ds_read_b64_tr_b16 v[82:83], v0 offset:12288
	ds_read_b64_tr_b16 v[84:85], v0 offset:14336
	s_andn2_b64 s[8:9], exec, s[0:1]
	s_andn2_b64 vcc, exec, s[0:1]
	s_cbranch_vccnz .Lh2_456
; template <bool FIRST, bool DOEXP = true>
; __device__ __forceinline__ void partialSM(f32x16& p0, f32x16& p1, float& m_reg, f32x16& negm, float& alpha, const bool track = true) {
;     ...
;   float pmax = p0[0];
; #pragma unroll
;   for (int r = 1; r < 16; ++r) pmax = fmaxf(pmax, p0[r]);
; #pragma unroll
;   for (int r = 0; r < 16; ++r) pmax = fmaxf(pmax, p1[r]);
;   { auto rr = __builtin_amdgcn_permlane32_swap(__float_as_uint(pmax), __float_as_uint(pmax), false, false);
;     pmax = fmaxf(__uint_as_float(rr[0]), __uint_as_float(rr[1])); }
;   if (!FIRST && __builtin_expect(__all(pmax <= THRL), 1)) { alpha = 1.f; }
;   else { const float dl = FIRST ? pmax : fmaxf(pmax, 0.f); m_reg += dl; alpha = FIRST ? 1.f : __builtin_amdgcn_exp2f(-dl);
; #pragma unroll
;     for (int r = 0; r < 16; ++r) { p0[r] -= dl; p1[r] -= dl; }
; #pragma unroll
;     for (int r = 0; r < 16; ++r) negm[r] = -m_reg;
;     asm volatile("" : "+v"(negm)); }
	v_max_f32_e32 v114, v132, v133
	v_max3_f32 v114, v114, v134, v135
	v_max3_f32 v114, v114, v136, v137
	v_max3_f32 v114, v114, v138, v139
	v_max3_f32 v114, v114, v140, v141
	v_max3_f32 v114, v114, v142, v143
	v_max3_f32 v114, v114, v144, v145
	v_max3_f32 v114, v114, v146, v147
	v_max3_f32 v114, v114, v98, v99
	v_max3_f32 v114, v114, v100, v101
	v_max3_f32 v114, v114, v102, v103
	v_max3_f32 v114, v114, v104, v105
	v_max3_f32 v114, v114, v106, v107
	v_max3_f32 v114, v114, v108, v109
	v_max3_f32 v114, v114, v110, v111
	v_max3_f32 v114, v114, v112, v113
	v_mov_b32_e32 v115, v114
	s_nop 1
	v_permlane32_swap_b32_e32 v114, v115
	v_max_f32_e32 v114, v114, v115
	v_cmp_ge_f32_e32 vcc, s69, v114
	s_cmp_eq_u64 vcc, exec
	v_mov_b32_e32 v130, 1.0
	s_cbranch_scc1 .Lh2_457
	v_max_f32_e32 v66, v114, v114
	v_max_f32_e32 v66, 0, v66
	v_exp_f32_e64 v130, -v66
	v_add_f32_e32 v222, v222, v66
	v_sub_f32_e32 v147, v147, v66
	v_sub_f32_e32 v146, v146, v66
	v_sub_f32_e32 v145, v145, v66
	v_sub_f32_e32 v144, v144, v66
	v_sub_f32_e32 v143, v143, v66
	v_sub_f32_e32 v142, v142, v66
	v_sub_f32_e32 v141, v141, v66
	v_sub_f32_e32 v140, v140, v66
	v_sub_f32_e32 v139, v139, v66
	v_sub_f32_e32 v138, v138, v66
	v_sub_f32_e32 v137, v137, v66
	v_sub_f32_e32 v136, v136, v66
	v_sub_f32_e32 v135, v135, v66
	v_sub_f32_e32 v134, v134, v66
	v_sub_f32_e32 v133, v133, v66
	v_sub_f32_e32 v132, v132, v66
	v_sub_f32_e32 v113, v113, v66
	v_sub_f32_e32 v112, v112, v66
	v_sub_f32_e32 v111, v111, v66
	v_sub_f32_e32 v110, v110, v66
	v_sub_f32_e32 v109, v109, v66
	v_sub_f32_e32 v108, v108, v66
	v_sub_f32_e32 v107, v107, v66
	v_sub_f32_e32 v106, v106, v66
	v_sub_f32_e32 v105, v105, v66
	v_sub_f32_e32 v104, v104, v66
	v_sub_f32_e32 v103, v103, v66
	v_sub_f32_e32 v102, v102, v66
	v_sub_f32_e32 v101, v101, v66
	v_sub_f32_e32 v100, v100, v66
	v_sub_f32_e32 v99, v99, v66
	v_sub_f32_e32 v98, v98, v66
	v_xor_b32_e32 v66, 0x80000000, v222
	v_mov_b32_e32 v67, v66
	v_mov_b32_e32 v68, v66
	v_mov_b32_e32 v69, v66
	v_mov_b32_e32 v70, v66
	v_mov_b32_e32 v71, v66
	v_mov_b32_e32 v72, v66
	v_mov_b32_e32 v73, v66
	v_mov_b32_e32 v74, v66
	v_mov_b32_e32 v75, v66
	v_mov_b32_e32 v76, v66
	v_mov_b32_e32 v77, v66
	v_mov_b32_e32 v78, v66
	v_mov_b32_e32 v79, v66
	v_mov_b32_e32 v80, v66
	v_mov_b32_e32 v81, v66
	s_branch .Lh2_457

; #define SBAR() __builtin_amdgcn_sched_barrier(0)
; __device__ __forceinline__ unsigned cvtpk(float lo, float hi) { unsigned r; asm volatile("v_cvt_pk_bf16_f32 %0, %1, %2" : "=v"(r) : "v"(lo), "v"(hi)); return r; }
; template <bool FIRST, bool DOEXP = true>
; __device__ __forceinline__ void partialSM(f32x16& p0, f32x16& p1, float& m_reg, f32x16& negm, float& alpha, const bool track = true) {
;     ...
;   float pmax = p0[0];
; #pragma unroll
;   for (int r = 1; r < 16; ++r) pmax = fmaxf(pmax, p0[r]);
; #pragma unroll
;   for (int r = 0; r < 16; ++r) pmax = fmaxf(pmax, p1[r]);
;   { auto rr = __builtin_amdgcn_permlane32_swap(__float_as_uint(pmax), __float_as_uint(pmax), false, false);
;     pmax = fmaxf(__uint_as_float(rr[0]), __uint_as_float(rr[1])); }
;   if (!FIRST && __builtin_expect(__all(pmax <= THRL), 1)) { alpha = 1.f; }
; __device__ __forceinline__ void qkt_fin(f32x16& n0, f32x16& n1, const bf16_t* Ks, const bf16x8* qr, const f32x16& negm, int r32, int hi, ...
;   float psa = 0.f, psb = 0.f; u32x4 wa, wb, wc, wd;
;     ...
; #pragma unroll
;   for (int d0 = 0; d0 < 8; ++d0) { int cb = (d0 * 16 + hi * 8) * 2;
;     bf16x8 b0 = *reinterpret_cast<const bf16x8*>((const char*)Ks + KSWZ(r32, cb));
;     bf16x8 b1 = *reinterpret_cast<const bf16x8*>((const char*)Ks + KSWZ(32 + r32, cb));
;     SBAR(); if (d0 == 0) n0 = __builtin_amdgcn_mfma_f32_32x32x16_bf16(b0, qr[0], negm, 0, 0, 0); else n0 = __builtin_amdgcn_mfma_f32_32x32x16_bf16(b0, qr[d0], n0, 0, 0, 0);
;     SBAR(); QF_CHUNK(2 * d0); SBAR();
;     if (d0 == 0) n1 = __builtin_amdgcn_mfma_f32_32x32x16_bf16(b1, qr[0], negm, 0, 0, 0); else n1 = __builtin_amdgcn_mfma_f32_32x32x16_bf16(b1, qr[d0], n1, 0, 0, 0);
;     SBAR(); QF_CHUNK(2 * d0 + 1); SBAR();
;     if (d0 == 7) { vf8_read<0>(vf0, vbv); SBAR(); } }
;     ...
;   psb += P1[15]; wd[3] = cvtpk(P1[14], P1[15]);
;   l_reg = l_reg * alpha + (psa + psb);
;   pa0 = *reinterpret_cast<bf16x8*>(&wa); pa1 = *reinterpret_cast<bf16x8*>(&wb); pa2 = *reinterpret_cast<bf16x8*>(&wc); pa3 = *reinterpret_cast<bf16x8*>(&wd);
; }
.Lh2_461:
	s_setprio 1
	s_waitcnt lgkmcnt(0)
	s_waitcnt vmcnt(0)
	s_barrier
	v_add_u32_e32 v208, s99, v236
	ds_read_b128 v[204:207], v208 offset:16384
	ds_read_b128 v[208:211], v208 offset:24576
	v_add_u32_e32 v252, s99, v237
	ds_read_b128 v[248:251], v252 offset:16384
	ds_read_b128 v[252:255], v252 offset:24576
	v_add_u32_e32 v203, s96, v235
	s_waitcnt lgkmcnt(3)
	v_mfma_f32_32x32x16_bf16 v[114:129], v[204:207], v[152:155], v[66:81]
	v_exp_f32_e32 v98, v98
	s_waitcnt lgkmcnt(2)
	v_mfma_f32_32x32x16_bf16 v[82:97], v[208:211], v[152:155], v[66:81]
	v_exp_f32_e32 v99, v99
	v_add_f32_e32 v201, v133, v132
	v_cvt_pk_bf16_f32 v132, v132, v133
	v_add_u32_e32 v208, s99, v238
	ds_read_b128 v[204:207], v208 offset:16384
	ds_read_b128 v[208:211], v208 offset:24576
	s_waitcnt lgkmcnt(3)
	v_mfma_f32_32x32x16_bf16 v[114:129], v[248:251], v[160:163], v[114:129]
	v_exp_f32_e32 v100, v100
	v_add_f32_e32 v201, v134, v201
	v_add_f32_e32 v202, v98, v99
	s_waitcnt lgkmcnt(2)
	v_mfma_f32_32x32x16_bf16 v[82:97], v[252:255], v[160:163], v[82:97]
	v_exp_f32_e32 v101, v101
	v_add_f32_e32 v201, v135, v201
	v_add_f32_e32 v202, v202, v100
	v_cvt_pk_bf16_f32 v133, v134, v135
	v_cvt_pk_bf16_f32 v196, v98, v99
	v_add_u32_e32 v252, s99, v239
	ds_read_b128 v[248:251], v252 offset:16384
	ds_read_b128 v[252:255], v252 offset:24576
	s_add_i32 s79, s98, s100
	s_add_i32 m0, s79, 0x4000
	s_add_i32 s79, s79, 0x6000
	global_load_lds_dwordx4 v180, s[82:83]
	s_waitcnt lgkmcnt(3)
	v_mfma_f32_32x32x16_bf16 v[114:129], v[204:207], v[148:151], v[114:129]
	v_exp_f32_e32 v102, v102
	v_add_f32_e32 v201, v136, v201
	v_add_f32_e32 v202, v202, v101
	s_waitcnt lgkmcnt(2)
	v_mfma_f32_32x32x16_bf16 v[82:97], v[208:211], v[148:151], v[82:97]
	v_exp_f32_e32 v103, v103
	v_add_f32_e32 v201, v137, v201
	v_add_f32_e32 v202, v202, v102
	v_cvt_pk_bf16_f32 v134, v136, v137
	v_cvt_pk_bf16_f32 v197, v100, v101
	v_add_u32_e32 v208, s99, v240
	ds_read_b128 v[204:207], v208 offset:16384
	ds_read_b128 v[208:211], v208 offset:24576
	s_mov_b32 m0, s79
	s_add_i32 s79, s98, s101
	global_load_lds_dwordx4 v182, s[82:83]
	s_waitcnt lgkmcnt(3)
	v_mfma_f32_32x32x16_bf16 v[114:129], v[248:251], v[156:159], v[114:129]
	v_exp_f32_e32 v104, v104
	v_add_f32_e32 v201, v138, v201
	v_add_f32_e32 v202, v202, v103
	s_waitcnt lgkmcnt(2)
	v_mfma_f32_32x32x16_bf16 v[82:97], v[252:255], v[156:159], v[82:97]
	v_exp_f32_e32 v105, v105
	v_add_f32_e32 v201, v139, v201
	v_add_f32_e32 v202, v202, v104
	v_cvt_pk_bf16_f32 v135, v138, v139
	v_cvt_pk_bf16_f32 v198, v102, v103
	v_add_u32_e32 v252, s99, v241
	ds_read_b128 v[248:251], v252 offset:16384
	ds_read_b128 v[252:255], v252 offset:24576
	s_mov_b32 m0, s79
	s_add_i32 s79, s79, 0x380
	global_load_lds_dwordx4 v214, s[82:83]
	s_waitcnt lgkmcnt(3)
	v_mfma_f32_32x32x16_bf16 v[114:129], v[204:207], v[168:171], v[114:129]
	v_exp_f32_e32 v106, v106
	v_add_f32_e32 v201, v140, v201
	v_add_f32_e32 v202, v202, v105
	s_waitcnt lgkmcnt(2)
	v_mfma_f32_32x32x16_bf16 v[82:97], v[208:211], v[168:171], v[82:97]
	v_exp_f32_e32 v107, v107
	v_add_f32_e32 v201, v141, v201
	v_add_f32_e32 v202, v202, v106
	v_cvt_pk_bf16_f32 v136, v140, v141
	v_cvt_pk_bf16_f32 v199, v104, v105
	v_add_u32_e32 v208, s99, v242
	ds_read_b128 v[204:207], v208 offset:16384
	ds_read_b128 v[208:211], v208 offset:24576
	s_mov_b32 m0, s79
	s_nop 0
	global_load_lds_dwordx4 v214, s[82:83] offset:128
	s_add_u32 s82, s82, s76
	s_addc_u32 s83, s83, s77
	s_waitcnt lgkmcnt(3)
	v_mfma_f32_32x32x16_bf16 v[114:129], v[248:251], v[176:179], v[114:129]
	v_exp_f32_e32 v108, v108
	v_add_f32_e32 v201, v142, v201
	v_add_f32_e32 v202, v202, v107
	s_waitcnt lgkmcnt(2)
	v_mfma_f32_32x32x16_bf16 v[82:97], v[252:255], v[176:179], v[82:97]
	v_exp_f32_e32 v109, v109
	v_add_f32_e32 v201, v143, v201
	v_add_f32_e32 v202, v202, v108
	v_cvt_pk_bf16_f32 v137, v142, v143
	v_cvt_pk_bf16_f32 v140, v106, v107
	v_add_u32_e32 v252, s99, v243
	ds_read_b128 v[248:251], v252 offset:16384
	ds_read_b128 v[252:255], v252 offset:24576
	s_waitcnt lgkmcnt(3)
	v_mfma_f32_32x32x16_bf16 v[114:129], v[204:207], v[164:167], v[114:129]
	v_exp_f32_e32 v110, v110
	v_add_f32_e32 v201, v144, v201
	v_add_f32_e32 v202, v202, v109
	s_waitcnt lgkmcnt(2)
	v_mfma_f32_32x32x16_bf16 v[82:97], v[208:211], v[164:167], v[82:97]
	v_exp_f32_e32 v111, v111
	v_add_f32_e32 v201, v145, v201
	v_add_f32_e32 v202, v202, v110
	v_cvt_pk_bf16_f32 v138, v144, v145
	v_cvt_pk_bf16_f32 v141, v108, v109
	s_waitcnt lgkmcnt(1)
	v_mfma_f32_32x32x16_bf16 v[114:129], v[248:251], v[172:175], v[114:129]
	v_exp_f32_e32 v112, v112
	v_add_f32_e32 v201, v146, v201
	v_add_f32_e32 v202, v202, v111
	s_waitcnt lgkmcnt(0)
	v_mfma_f32_32x32x16_bf16 v[82:97], v[252:255], v[172:175], v[82:97]
	v_exp_f32_e32 v113, v113
	v_add_f32_e32 v201, v147, v201
	v_add_f32_e32 v202, v202, v112
	v_cvt_pk_bf16_f32 v139, v146, v147
	v_cvt_pk_bf16_f32 v142, v110, v111
	ds_read_b64_tr_b16 v[144:145], v203 offset:0
	ds_read_b64_tr_b16 v[146:147], v203 offset:2048
	s_nop 0
	ds_read_b64_tr_b16 v[106:107], v203 offset:4096
	ds_read_b64_tr_b16 v[108:109], v203 offset:6144
	ds_read_b64_tr_b16 v[102:103], v203 offset:8192
	ds_read_b64_tr_b16 v[104:105], v203 offset:10240
	ds_read_b64_tr_b16 v[98:99], v203 offset:12288
	ds_read_b64_tr_b16 v[100:101], v203 offset:14336
	v_cvt_pk_bf16_f32 v143, v112, v113
	s_and_b64 vcc, exec, s[8:9]
	v_mov_b32_e32 v200, 1.0
	s_cbranch_vccnz .Lh2_463
	v_max_f32_e32 v110, v114, v115
	v_max3_f32 v110, v110, v116, v117
	v_max3_f32 v110, v110, v118, v119
	v_max3_f32 v110, v110, v120, v121
	v_max3_f32 v110, v110, v122, v123
	v_max3_f32 v110, v110, v124, v125
	v_max3_f32 v110, v110, v126, v127
	v_max3_f32 v110, v110, v128, v129
	v_max3_f32 v110, v110, v82, v83
	v_max3_f32 v110, v110, v84, v85
	v_max3_f32 v110, v110, v86, v87
	v_max3_f32 v110, v110, v88, v89
	v_max3_f32 v110, v110, v90, v91
	v_max3_f32 v110, v110, v92, v93
	v_max3_f32 v110, v110, v94, v95
	v_max3_f32 v110, v110, v96, v97
	v_mov_b32_e32 v111, v110
	s_nop 1
	v_permlane32_swap_b32_e32 v110, v111
	v_max_f32_e32 v110, v110, v111
	v_cmp_ge_f32_e32 vcc, s69, v110
	s_cmp_eq_u64 vcc, exec
	v_mov_b32_e32 v200, 1.0
	s_cbranch_scc0 .Lh2_469
